# fix1 + ret_out/outproj-epilogue load de-serialization + pipelined in-proj K loop
# speedup vs baseline: 1.0217x; 1.0217x over previous
; #define WAIT_V(n) asm volatile("s_waitcnt vmcnt(" #n ")" ::: "memory")
; #define BAR __builtin_amdgcn_s_barrier()
; #define LDA_(dst, ai) _Pragma("unroll") for (int m = 0; m < 4; ++m) dst[m] = *(const bf16x8*)(sb + (ai) * 8192 + la0 + m * 1024)
; #define LDB_(dst) _Pragma("unroll") for (int bj = 0; bj < 2; ++bj) _Pragma("unroll") for (int n = 0; n < 2; ++n) dst[bj][n] = *(const bf16x8*)(sb + 16384 + bj * 8192 + lb0 + n * 1024)
; template <int MODE>
; DI void gemm_phase(const Params& p, int layer, int hf, unsigned char* shmc, int tid) {
;     ...
;     const bf16_t* gA = (MODE == 0) ? A + (size_t)(brow >> 7) * nt * 4096 : A + (size_t)brow * lda; const bf16_t* gB = Bt + (size_t)(bcol >> 7) * nt * 4096;
;     ...
;     if (!pre) { STAGE_ALL(0, 0); STAGE_ALL(1, 1); }
;     STAGE_ALL(2, 2);
;     for (int kt = 0; kt < nt; ++kt) {
;       const int rem = nt - 1 - kt;
;       if (rem >= 2) WAIT_V(8); else if (rem == 1) WAIT_V(4); else WAIT_V(0);
;       BAR;
;       const unsigned char* sb = shmc + (kt & 3) * 32768;
;     ...
;       {
;         bf16x8 b0[2][2], a0[4], a1[4];
;         LDB_(b0); LDA_(a0, 0);
.LBB0_156:
	s_lshl_b32 s10, s27, 1
	s_ashr_i32 s11, s10, 31
	s_lshl_b64 s[10:11], s[10:11], 18
	s_add_u32 s14, s2, s10
	v_mov_b32_e32 v0, v172
	s_addc_u32 s15, s20, s11
	s_lshl_b32 s16, s26, 1
	s_ashr_i32 s17, s16, 31
	v_lshl_add_u32 v4, v0, 4, 32
	v_lshlrev_b32_e32 v0, 3, v0
	s_lshl_b64 s[16:17], s[16:17], 18
	v_readlane_b32 s18, v254, 22
	v_ashrrev_i32_e32 v1, 31, v0
	s_add_u32 s18, s18, s16
	v_readlane_b32 s19, v254, 23
	v_lshlrev_b64 v[0:1], 1, v[0:1]
	v_add_u32_e32 v5, 0x4000, v4
	v_readfirstlane_b32 s28, v4
	s_addc_u32 s19, s19, s17
	v_lshl_add_u64 v[2:3], s[14:15], 0, v[0:1]
	s_mov_b32 m0, s28
	v_readfirstlane_b32 s28, v5
	v_add_u32_e32 v5, 0x2000, v4
	v_lshl_add_u64 v[0:1], s[18:19], 0, v[0:1]
	global_load_lds_dwordx4 v[2:3], off
	s_mov_b32 m0, s28
	s_mov_b64 s[40:41], 0x40000
	v_readfirstlane_b32 s28, v5
	global_load_lds_dwordx4 v[0:1], off
	v_lshl_add_u64 v[2:3], v[2:3], 0, s[40:41]
	s_mov_b32 m0, s28
	v_lshl_add_u64 v[0:1], v[0:1], 0, s[40:41]
	global_load_lds_dwordx4 v[2:3], off
	v_add_u32_e32 v2, 0x6000, v4
	s_mov_b64 s[40:41], 0x2000
	v_readfirstlane_b32 s28, v2
	s_mov_b32 m0, s28
	s_add_u32 s10, s13, s10
	global_load_lds_dwordx4 v[0:1], off
	v_mov_b32_e32 v0, v172
	s_addc_u32 s11, s23, s11
	v_lshl_add_u32 v6, v0, 4, 32
	v_lshlrev_b32_e32 v0, 3, v0
	v_ashrrev_i32_e32 v1, 31, v0
	v_add_u32_e32 v7, 0x8000, v6
	v_lshlrev_b64 v[0:1], 1, v[0:1]
	v_lshl_add_u64 v[2:3], s[14:15], 0, v[0:1]
	v_add_u32_e32 v8, 0xc000, v6
	v_readfirstlane_b32 s28, v7
	v_lshl_add_u64 v[0:1], s[18:19], 0, v[0:1]
	v_lshl_add_u64 v[4:5], v[2:3], 0, s[40:41]
	s_mov_b32 m0, s28
	v_readfirstlane_b32 s28, v8
	global_load_lds_dwordx4 v[4:5], off
	v_lshl_add_u64 v[4:5], v[0:1], 0, s[40:41]
	s_mov_b32 m0, s28
	s_mov_b64 s[40:41], 0x42000
	global_load_lds_dwordx4 v[4:5], off
	v_add_u32_e32 v4, 0xa000, v6
	v_lshl_add_u64 v[2:3], v[2:3], 0, s[40:41]
	v_readfirstlane_b32 s28, v4
	s_mov_b32 m0, s28
	v_lshl_add_u64 v[0:1], v[0:1], 0, s[40:41]
	global_load_lds_dwordx4 v[2:3], off
	v_add_u32_e32 v2, 0xe000, v6
	s_mov_b32 s29, 0x18000
	v_readfirstlane_b32 s28, v2
	s_mov_b32 m0, s28
	v_readlane_b32 s28, v253, 62
	global_load_lds_dwordx4 v[0:1], off
	v_mov_b32_e32 v0, v172
	s_nop 0
	v_lshl_add_u32 v6, v0, 4, s28
	v_lshlrev_b32_e32 v0, 3, v0
	v_ashrrev_i32_e32 v1, 31, v0
	v_lshlrev_b64 v[0:1], 1, v[0:1]
	v_lshl_add_u64 v[2:3], s[14:15], 0, v[0:1]
	v_lshl_add_u64 v[0:1], s[18:19], 0, v[0:1]
	v_add_u32_e32 v7, 0x4000, v6
	s_mov_b64 s[18:19], 0x4000
	v_readfirstlane_b32 s14, v6
	v_lshl_add_u64 v[4:5], v[2:3], 0, s[18:19]
	s_mov_b32 m0, s14
	v_readfirstlane_b32 s14, v7
	global_load_lds_dwordx4 v[4:5], off
	v_lshl_add_u64 v[4:5], v[0:1], 0, s[18:19]
	s_mov_b32 m0, s14
	s_mov_b64 s[18:19], 0x44000
	global_load_lds_dwordx4 v[4:5], off
	v_add_u32_e32 v4, 0x2000, v6
	v_lshl_add_u64 v[2:3], v[2:3], 0, s[18:19]
	v_readfirstlane_b32 s14, v4
	s_mov_b32 m0, s14
	v_lshl_add_u64 v[0:1], v[0:1], 0, s[18:19]
	global_load_lds_dwordx4 v[2:3], off
	v_add_u32_e32 v2, 0x6000, v6
	s_mov_b32 s28, 0
	v_readfirstlane_b32 s14, v2
	s_mov_b32 m0, s14
	v_readlane_b32 s14, v254, 7
	global_load_lds_dwordx4 v[0:1], off
	v_readlane_b32 s15, v254, 8
	s_add_u32 s14, s14, s16
	v_mov_b32_e32 v0, 0
	s_addc_u32 s15, s15, s17
	s_mov_b64 s[16:17], 0
	v_mov_b32_e32 v1, v0
	v_mov_b32_e32 v2, v0
	v_mov_b32_e32 v3, v0
	v_mov_b32_e32 v4, v0
	v_mov_b32_e32 v5, v0
	v_mov_b32_e32 v6, v0
	v_mov_b32_e32 v7, v0
	v_mov_b32_e32 v24, v0
	v_mov_b32_e32 v25, v0
	v_mov_b32_e32 v26, v0
	v_mov_b32_e32 v27, v0
	v_mov_b32_e32 v36, v0
	v_mov_b32_e32 v37, v0
	v_mov_b32_e32 v38, v0
	v_mov_b32_e32 v39, v0
	v_mov_b32_e32 v56, v0
	v_mov_b32_e32 v57, v0
	v_mov_b32_e32 v58, v0
	v_mov_b32_e32 v59, v0
	v_mov_b32_e32 v68, v0
	v_mov_b32_e32 v69, v0
	v_mov_b32_e32 v70, v0
	v_mov_b32_e32 v71, v0
	v_mov_b32_e32 v72, v0
	v_mov_b32_e32 v73, v0
	v_mov_b32_e32 v74, v0
	v_mov_b32_e32 v75, v0
	v_mov_b32_e32 v80, v0
	v_mov_b32_e32 v81, v0
	v_mov_b32_e32 v82, v0
	v_mov_b32_e32 v83, v0
	v_mov_b32_e32 v88, v0
	v_mov_b32_e32 v89, v0
	v_mov_b32_e32 v90, v0
	v_mov_b32_e32 v91, v0
	v_mov_b32_e32 v96, v0
	v_mov_b32_e32 v97, v0
	v_mov_b32_e32 v98, v0
	v_mov_b32_e32 v99, v0
	v_mov_b32_e32 v104, v0
	v_mov_b32_e32 v105, v0
	v_mov_b32_e32 v106, v0
	v_mov_b32_e32 v107, v0
	v_mov_b32_e32 v112, v0
	v_mov_b32_e32 v113, v0
	v_mov_b32_e32 v114, v0
	v_mov_b32_e32 v115, v0
	v_mov_b32_e32 v76, v0
	v_mov_b32_e32 v77, v0
	v_mov_b32_e32 v78, v0
	v_mov_b32_e32 v79, v0
	v_mov_b32_e32 v84, v0
	v_mov_b32_e32 v85, v0
	v_mov_b32_e32 v86, v0
	v_mov_b32_e32 v87, v0
	v_mov_b32_e32 v92, v0
	v_mov_b32_e32 v93, v0
	v_mov_b32_e32 v94, v0
	v_mov_b32_e32 v95, v0
	v_mov_b32_e32 v100, v0
	v_mov_b32_e32 v101, v0
	v_mov_b32_e32 v102, v0
	v_mov_b32_e32 v103, v0
	v_mov_b32_e32 v108, v0
	v_mov_b32_e32 v109, v0
	v_mov_b32_e32 v110, v0
	v_mov_b32_e32 v111, v0
	v_mov_b32_e32 v116, v0
	v_mov_b32_e32 v117, v0
	v_mov_b32_e32 v118, v0
	v_mov_b32_e32 v119, v0
	v_mov_b32_e32 v120, v0
	v_mov_b32_e32 v121, v0
	v_mov_b32_e32 v122, v0
	v_mov_b32_e32 v123, v0
	v_mov_b32_e32 v124, v0
	v_mov_b32_e32 v125, v0
	v_mov_b32_e32 v126, v0
	v_mov_b32_e32 v127, v0
	v_mov_b32_e32 v32, v0
	v_mov_b32_e32 v33, v0
	v_mov_b32_e32 v34, v0
	v_mov_b32_e32 v35, v0
	v_mov_b32_e32 v28, v0
	v_mov_b32_e32 v29, v0
	v_mov_b32_e32 v30, v0
	v_mov_b32_e32 v31, v0
	v_mov_b32_e32 v12, v0
	v_mov_b32_e32 v13, v0
	v_mov_b32_e32 v14, v0
	v_mov_b32_e32 v15, v0
	v_mov_b32_e32 v8, v0
	v_mov_b32_e32 v9, v0
	v_mov_b32_e32 v10, v0
	v_mov_b32_e32 v11, v0
	v_mov_b32_e32 v64, v0
	v_mov_b32_e32 v65, v0
	v_mov_b32_e32 v66, v0
	v_mov_b32_e32 v67, v0
	v_mov_b32_e32 v60, v0
	v_mov_b32_e32 v61, v0
	v_mov_b32_e32 v62, v0
	v_mov_b32_e32 v63, v0
	v_mov_b32_e32 v52, v0
	v_mov_b32_e32 v53, v0
	v_mov_b32_e32 v54, v0
	v_mov_b32_e32 v55, v0
	v_mov_b32_e32 v48, v0
	v_mov_b32_e32 v49, v0
	v_mov_b32_e32 v50, v0
	v_mov_b32_e32 v51, v0
	v_mov_b32_e32 v44, v0
	v_mov_b32_e32 v45, v0
	v_mov_b32_e32 v46, v0
	v_mov_b32_e32 v47, v0
	v_mov_b32_e32 v40, v0
	v_mov_b32_e32 v41, v0
	v_mov_b32_e32 v42, v0
	v_mov_b32_e32 v43, v0
	v_mov_b32_e32 v20, v0
	v_mov_b32_e32 v21, v0
	v_mov_b32_e32 v22, v0
	v_mov_b32_e32 v23, v0
	v_mov_b32_e32 v16, v0
	v_mov_b32_e32 v17, v0
	v_mov_b32_e32 v18, v0
	v_mov_b32_e32 v19, v0
	v_lshlrev_b32_e32 v160, 4, v172
	v_add_u32_e32 v191, 32, v178
	v_add_u32_e32 v192, 0x10020, v178
	v_readfirstlane_b32 s29, v160
	v_add3_u32 v194, v179, v164, 32
	s_add_u32 s98, s10, 0xd006000
	s_addc_u32 s99, s11, 0
	s_add_u32 s100, s14, 0x11006000
	s_addc_u32 s101, s15, 0
	v_add_u32_e32 v202, 0x10000, v194
	s_add_i32 s29, s29, 32
	s_mov_b32 s28, 0
	s_waitcnt vmcnt(8)
	s_barrier
	ds_read_b128 v[140:143], v194 offset:16384
	ds_read_b128 v[144:147], v194 offset:17408
	ds_read_b128 v[136:139], v194 offset:24576
	ds_read_b128 v[128:131], v194 offset:25600
	ds_read_b128 v[132:135], v191
	ds_read_b128 v[148:151], v191 offset:1024
	ds_read_b128 v[152:155], v191 offset:2048
	ds_read_b128 v[204:207], v191 offset:3072
; #define WAIT_V(n) asm volatile("s_waitcnt vmcnt(" #n ")" ::: "memory")
; #define BAR __builtin_amdgcn_s_barrier()
; #define LDA_(dst, ai) _Pragma("unroll") for (int m = 0; m < 4; ++m) dst[m] = *(const bf16x8*)(sb + (ai) * 8192 + la0 + m * 1024)
; #define LDB_(dst) _Pragma("unroll") for (int bj = 0; bj < 2; ++bj) _Pragma("unroll") for (int n = 0; n < 2; ++n) dst[bj][n] = *(const bf16x8*)(sb + 16384 + bj * 8192 + lb0 + n * 1024)
; #define MMA_(ai, bf_, af_) _Pragma("unroll") for (int bj = 0; bj < 2; ++bj) _Pragma("unroll") for (int m = 0; m < 4; ++m) _Pragma("unroll") for (int n = 0; n < 2; ++n) \
;         acc[ai][bj][m][n] = __builtin_amdgcn_mfma_f32_16x16x32_bf16(bf_[bj][n], af_[m], acc[ai][bj][m][n], 0, 0, 0)
; template <int MODE>
; DI void gemm_phase(const Params& p, int layer, int hf, unsigned char* shmc, int tid) {
;     ...
;     for (int kt = 0; kt < nt; ++kt) {
;       const int rem = nt - 1 - kt;
;       if (rem >= 2) WAIT_V(8); else if (rem == 1) WAIT_V(4); else WAIT_V(0);
;       BAR;
;       const unsigned char* sb = shmc + (kt & 3) * 32768;
;     ...
;       {
;         bf16x8 b0[2][2], a0[4], a1[4];
;         LDB_(b0); LDA_(a0, 0);
;         __builtin_amdgcn_sched_barrier(0);
;         LDA_(a1, 1); MMA_(0, b0, a0);
;         __builtin_amdgcn_sched_barrier(0);
;         if (kt + 3 < nt) STAGE_ALL((kt + 3) & 3, kt + 3);
;         __builtin_amdgcn_sched_barrier(0);
;         MMA_(1, b0, a1);
;       }
.Lg0_loop:
	s_waitcnt vmcnt(4)
	s_barrier
	ds_read_b128 v[156:159], v191 offset:8192
	ds_read_b128 v[240:243], v191 offset:9216
	ds_read_b128 v[244:247], v191 offset:10240
	ds_read_b128 v[248:251], v191 offset:11264
	s_waitcnt lgkmcnt(4)
	v_mfma_f32_16x16x32_bf16 v[124:127], v[140:143], v[132:135], v[124:127]
	v_mfma_f32_16x16x32_bf16 v[120:123], v[144:147], v[132:135], v[120:123]
	ds_read_b128 v[208:211], v194 offset:49152
	v_mfma_f32_16x16x32_bf16 v[116:119], v[140:143], v[148:151], v[116:119]
	v_mfma_f32_16x16x32_bf16 v[108:111], v[144:147], v[148:151], v[108:111]
	ds_read_b128 v[212:215], v194 offset:50176
	v_mfma_f32_16x16x32_bf16 v[100:103], v[140:143], v[152:155], v[100:103]
	v_mfma_f32_16x16x32_bf16 v[92:95], v[144:147], v[152:155], v[92:95]
	ds_read_b128 v[216:219], v194 offset:57344
	v_mfma_f32_16x16x32_bf16 v[112:115], v[136:139], v[132:135], v[112:115]
	v_mfma_f32_16x16x32_bf16 v[104:107], v[128:131], v[132:135], v[104:107]
	ds_read_b128 v[220:223], v194 offset:58368
	v_mfma_f32_16x16x32_bf16 v[96:99], v[136:139], v[148:151], v[96:99]
	v_mfma_f32_16x16x32_bf16 v[88:91], v[128:131], v[148:151], v[88:91]
	ds_read_b128 v[224:227], v191 offset:32768
	v_mfma_f32_16x16x32_bf16 v[80:83], v[136:139], v[152:155], v[80:83]
	v_mfma_f32_16x16x32_bf16 v[72:75], v[128:131], v[152:155], v[72:75]
	ds_read_b128 v[228:231], v191 offset:33792
	v_mfma_f32_16x16x32_bf16 v[84:87], v[140:143], v[204:207], v[84:87]
	v_mfma_f32_16x16x32_bf16 v[76:79], v[144:147], v[204:207], v[76:79]
	ds_read_b128 v[232:235], v191 offset:34816
	v_mfma_f32_16x16x32_bf16 v[68:71], v[136:139], v[204:207], v[68:71]
	v_mfma_f32_16x16x32_bf16 v[56:59], v[128:131], v[204:207], v[56:59]
	ds_read_b128 v[236:239], v191 offset:35840
	s_add_u32 m0, s29, 0x18000
	s_add_u32 s18, s98, 0x40000
	s_addc_u32 s19, s99, 0
	global_load_lds_dwordx4 v160, s[98:99]
	s_add_u32 m0, s29, 0x1c000
	s_add_u32 s16, s100, 0x40000
	s_addc_u32 s17, s101, 0
	global_load_lds_dwordx4 v160, s[100:101]
	s_add_u32 m0, s29, 0x1a000
	s_add_u32 s98, s98, 0x2000
	s_addc_u32 s99, s99, 0
	global_load_lds_dwordx4 v160, s[18:19]
	s_add_u32 m0, s29, 0x1e000
	s_add_u32 s100, s100, 0x2000
	s_addc_u32 s101, s101, 0
	global_load_lds_dwordx4 v160, s[16:17]
	s_waitcnt lgkmcnt(8)
	v_mfma_f32_16x16x32_bf16 v[36:39], v[140:143], v[156:159], v[36:39]
	v_mfma_f32_16x16x32_bf16 v[24:27], v[144:147], v[156:159], v[24:27]
	v_mfma_f32_16x16x32_bf16 v[4:7], v[140:143], v[240:243], v[4:7]
	v_mfma_f32_16x16x32_bf16 v[0:3], v[144:147], v[240:243], v[0:3]
	v_mfma_f32_16x16x32_bf16 v[32:35], v[140:143], v[244:247], v[32:35]
	v_mfma_f32_16x16x32_bf16 v[28:31], v[144:147], v[244:247], v[28:31]
	v_mfma_f32_16x16x32_bf16 v[12:15], v[140:143], v[248:251], v[12:15]
	v_mfma_f32_16x16x32_bf16 v[8:11], v[144:147], v[248:251], v[8:11]
	v_mfma_f32_16x16x32_bf16 v[64:67], v[136:139], v[156:159], v[64:67]
	v_mfma_f32_16x16x32_bf16 v[60:63], v[128:131], v[156:159], v[60:63]
	v_mfma_f32_16x16x32_bf16 v[52:55], v[136:139], v[240:243], v[52:55]
	v_mfma_f32_16x16x32_bf16 v[48:51], v[128:131], v[240:243], v[48:51]
	v_mfma_f32_16x16x32_bf16 v[44:47], v[136:139], v[244:247], v[44:47]
	v_mfma_f32_16x16x32_bf16 v[40:43], v[128:131], v[244:247], v[40:43]
	v_mfma_f32_16x16x32_bf16 v[20:23], v[136:139], v[248:251], v[20:23]
	v_mfma_f32_16x16x32_bf16 v[16:19], v[128:131], v[248:251], v[16:19]
	s_waitcnt vmcnt(4)
	s_barrier
	ds_read_b128 v[156:159], v191 offset:40960
	ds_read_b128 v[240:243], v191 offset:41984
	ds_read_b128 v[244:247], v191 offset:43008
	ds_read_b128 v[248:251], v191 offset:44032
	s_waitcnt lgkmcnt(4)
	v_mfma_f32_16x16x32_bf16 v[124:127], v[208:211], v[224:227], v[124:127]
	v_mfma_f32_16x16x32_bf16 v[120:123], v[212:215], v[224:227], v[120:123]
	ds_read_b128 v[140:143], v202 offset:16384
	v_mfma_f32_16x16x32_bf16 v[116:119], v[208:211], v[228:231], v[116:119]
	v_mfma_f32_16x16x32_bf16 v[108:111], v[212:215], v[228:231], v[108:111]
	ds_read_b128 v[144:147], v202 offset:17408
	v_mfma_f32_16x16x32_bf16 v[100:103], v[208:211], v[232:235], v[100:103]
	v_mfma_f32_16x16x32_bf16 v[92:95], v[212:215], v[232:235], v[92:95]
	ds_read_b128 v[136:139], v202 offset:24576
	v_mfma_f32_16x16x32_bf16 v[112:115], v[216:219], v[224:227], v[112:115]
	v_mfma_f32_16x16x32_bf16 v[104:107], v[220:223], v[224:227], v[104:107]
	ds_read_b128 v[128:131], v202 offset:25600
	v_mfma_f32_16x16x32_bf16 v[96:99], v[216:219], v[228:231], v[96:99]
	v_mfma_f32_16x16x32_bf16 v[88:91], v[220:223], v[228:231], v[88:91]
	ds_read_b128 v[132:135], v192
	v_mfma_f32_16x16x32_bf16 v[80:83], v[216:219], v[232:235], v[80:83]
	v_mfma_f32_16x16x32_bf16 v[72:75], v[220:223], v[232:235], v[72:75]
	ds_read_b128 v[148:151], v192 offset:1024
	v_mfma_f32_16x16x32_bf16 v[84:87], v[208:211], v[236:239], v[84:87]
	v_mfma_f32_16x16x32_bf16 v[76:79], v[212:215], v[236:239], v[76:79]
	ds_read_b128 v[152:155], v192 offset:2048
	v_mfma_f32_16x16x32_bf16 v[68:71], v[216:219], v[236:239], v[68:71]
	v_mfma_f32_16x16x32_bf16 v[56:59], v[220:223], v[236:239], v[56:59]
	ds_read_b128 v[204:207], v192 offset:3072
	s_cmp_ge_u32 s28, 28
	s_cbranch_scc1 .Lg0_nost_1
	s_mov_b32 m0, s29
	s_add_u32 s18, s98, 0x40000
	s_addc_u32 s19, s99, 0
	global_load_lds_dwordx4 v160, s[98:99]
	s_add_u32 m0, s29, 0x4000
	s_add_u32 s16, s100, 0x40000
	s_addc_u32 s17, s101, 0
	global_load_lds_dwordx4 v160, s[100:101]
	s_add_u32 m0, s29, 0x2000
	s_add_u32 s98, s98, 0x2000
	s_addc_u32 s99, s99, 0
	global_load_lds_dwordx4 v160, s[18:19]
	s_add_u32 m0, s29, 0x6000
	s_add_u32 s100, s100, 0x2000
	s_addc_u32 s101, s101, 0
	global_load_lds_dwordx4 v160, s[16:17]
; #define WAIT_V(n) asm volatile("s_waitcnt vmcnt(" #n ")" ::: "memory")
; #define BAR __builtin_amdgcn_s_barrier()
; #define LDA_(dst, ai) _Pragma("unroll") for (int m = 0; m < 4; ++m) dst[m] = *(const bf16x8*)(sb + (ai) * 8192 + la0 + m * 1024)
; #define LDB_(dst) _Pragma("unroll") for (int bj = 0; bj < 2; ++bj) _Pragma("unroll") for (int n = 0; n < 2; ++n) dst[bj][n] = *(const bf16x8*)(sb + 16384 + bj * 8192 + lb0 + n * 1024)
; #define MMA_(ai, bf_, af_) _Pragma("unroll") for (int bj = 0; bj < 2; ++bj) _Pragma("unroll") for (int m = 0; m < 4; ++m) _Pragma("unroll") for (int n = 0; n < 2; ++n) \
;         acc[ai][bj][m][n] = __builtin_amdgcn_mfma_f32_16x16x32_bf16(bf_[bj][n], af_[m], acc[ai][bj][m][n], 0, 0, 0)
; template <int MODE>
; DI void gemm_phase(const Params& p, int layer, int hf, unsigned char* shmc, int tid) {
;     ...
;     for (int kt = 0; kt < nt; ++kt) {
;       const int rem = nt - 1 - kt;
;       if (rem >= 2) WAIT_V(8); else if (rem == 1) WAIT_V(4); else WAIT_V(0);
;       BAR;
;       const unsigned char* sb = shmc + (kt & 3) * 32768;
;     ...
;       {
;         bf16x8 b0[2][2], a0[4], a1[4];
;         LDB_(b0); LDA_(a0, 0);
;         __builtin_amdgcn_sched_barrier(0);
;         LDA_(a1, 1); MMA_(0, b0, a0);
;         __builtin_amdgcn_sched_barrier(0);
;         if (kt + 3 < nt) STAGE_ALL((kt + 3) & 3, kt + 3);
;         __builtin_amdgcn_sched_barrier(0);
;         MMA_(1, b0, a1);
;       }
.Lg0_nost_1:
	s_waitcnt lgkmcnt(8)
	v_mfma_f32_16x16x32_bf16 v[36:39], v[208:211], v[156:159], v[36:39]
	v_mfma_f32_16x16x32_bf16 v[24:27], v[212:215], v[156:159], v[24:27]
	v_mfma_f32_16x16x32_bf16 v[4:7], v[208:211], v[240:243], v[4:7]
	v_mfma_f32_16x16x32_bf16 v[0:3], v[212:215], v[240:243], v[0:3]
	v_mfma_f32_16x16x32_bf16 v[32:35], v[208:211], v[244:247], v[32:35]
	v_mfma_f32_16x16x32_bf16 v[28:31], v[212:215], v[244:247], v[28:31]
	v_mfma_f32_16x16x32_bf16 v[12:15], v[208:211], v[248:251], v[12:15]
	v_mfma_f32_16x16x32_bf16 v[8:11], v[212:215], v[248:251], v[8:11]
	v_mfma_f32_16x16x32_bf16 v[64:67], v[216:219], v[156:159], v[64:67]
	v_mfma_f32_16x16x32_bf16 v[60:63], v[220:223], v[156:159], v[60:63]
	v_mfma_f32_16x16x32_bf16 v[52:55], v[216:219], v[240:243], v[52:55]
	v_mfma_f32_16x16x32_bf16 v[48:51], v[220:223], v[240:243], v[48:51]
	v_mfma_f32_16x16x32_bf16 v[44:47], v[216:219], v[244:247], v[44:47]
	v_mfma_f32_16x16x32_bf16 v[40:43], v[220:223], v[244:247], v[40:43]
	v_mfma_f32_16x16x32_bf16 v[20:23], v[216:219], v[248:251], v[20:23]
	v_mfma_f32_16x16x32_bf16 v[16:19], v[220:223], v[248:251], v[16:19]
	s_cmp_lt_u32 s28, 28
	s_cbranch_scc1 .Lg0_w4_2
	s_waitcnt vmcnt(0)
.Lg0_w4_2:
	s_waitcnt vmcnt(4)
	s_barrier
	ds_read_b128 v[156:159], v192 offset:8192
	ds_read_b128 v[240:243], v192 offset:9216
	ds_read_b128 v[244:247], v192 offset:10240
	ds_read_b128 v[248:251], v192 offset:11264
	s_waitcnt lgkmcnt(4)
	v_mfma_f32_16x16x32_bf16 v[124:127], v[140:143], v[132:135], v[124:127]
	v_mfma_f32_16x16x32_bf16 v[120:123], v[144:147], v[132:135], v[120:123]
	ds_read_b128 v[208:211], v202 offset:49152
	v_mfma_f32_16x16x32_bf16 v[116:119], v[140:143], v[148:151], v[116:119]
	v_mfma_f32_16x16x32_bf16 v[108:111], v[144:147], v[148:151], v[108:111]
	ds_read_b128 v[212:215], v202 offset:50176
	v_mfma_f32_16x16x32_bf16 v[100:103], v[140:143], v[152:155], v[100:103]
	v_mfma_f32_16x16x32_bf16 v[92:95], v[144:147], v[152:155], v[92:95]
	ds_read_b128 v[216:219], v202 offset:57344
	v_mfma_f32_16x16x32_bf16 v[112:115], v[136:139], v[132:135], v[112:115]
	v_mfma_f32_16x16x32_bf16 v[104:107], v[128:131], v[132:135], v[104:107]
	ds_read_b128 v[220:223], v202 offset:58368
	v_mfma_f32_16x16x32_bf16 v[96:99], v[136:139], v[148:151], v[96:99]
	v_mfma_f32_16x16x32_bf16 v[88:91], v[128:131], v[148:151], v[88:91]
	ds_read_b128 v[224:227], v192 offset:32768
	v_mfma_f32_16x16x32_bf16 v[80:83], v[136:139], v[152:155], v[80:83]
	v_mfma_f32_16x16x32_bf16 v[72:75], v[128:131], v[152:155], v[72:75]
	ds_read_b128 v[228:231], v192 offset:33792
	v_mfma_f32_16x16x32_bf16 v[84:87], v[140:143], v[204:207], v[84:87]
	v_mfma_f32_16x16x32_bf16 v[76:79], v[144:147], v[204:207], v[76:79]
	ds_read_b128 v[232:235], v192 offset:34816
	v_mfma_f32_16x16x32_bf16 v[68:71], v[136:139], v[204:207], v[68:71]
	v_mfma_f32_16x16x32_bf16 v[56:59], v[128:131], v[204:207], v[56:59]
	ds_read_b128 v[236:239], v192 offset:35840
	s_cmp_ge_u32 s28, 28
	s_cbranch_scc1 .Lg0_nost_2
	s_add_u32 m0, s29, 0x8000
	s_add_u32 s18, s98, 0x40000
	s_addc_u32 s19, s99, 0
	global_load_lds_dwordx4 v160, s[98:99]
	s_add_u32 m0, s29, 0xc000
	s_add_u32 s16, s100, 0x40000
	s_addc_u32 s17, s101, 0
	global_load_lds_dwordx4 v160, s[100:101]
	s_add_u32 m0, s29, 0xa000
	s_add_u32 s98, s98, 0x2000
	s_addc_u32 s99, s99, 0
	global_load_lds_dwordx4 v160, s[18:19]
	s_add_u32 m0, s29, 0xe000
	s_add_u32 s100, s100, 0x2000
	s_addc_u32 s101, s101, 0
	global_load_lds_dwordx4 v160, s[16:17]
.Lg0_nost_2:
	s_waitcnt lgkmcnt(8)
	v_mfma_f32_16x16x32_bf16 v[36:39], v[140:143], v[156:159], v[36:39]
	v_mfma_f32_16x16x32_bf16 v[24:27], v[144:147], v[156:159], v[24:27]
	v_mfma_f32_16x16x32_bf16 v[4:7], v[140:143], v[240:243], v[4:7]
	v_mfma_f32_16x16x32_bf16 v[0:3], v[144:147], v[240:243], v[0:3]
	v_mfma_f32_16x16x32_bf16 v[32:35], v[140:143], v[244:247], v[32:35]
	v_mfma_f32_16x16x32_bf16 v[28:31], v[144:147], v[244:247], v[28:31]
	v_mfma_f32_16x16x32_bf16 v[12:15], v[140:143], v[248:251], v[12:15]
	v_mfma_f32_16x16x32_bf16 v[8:11], v[144:147], v[248:251], v[8:11]
	v_mfma_f32_16x16x32_bf16 v[64:67], v[136:139], v[156:159], v[64:67]
	v_mfma_f32_16x16x32_bf16 v[60:63], v[128:131], v[156:159], v[60:63]
	v_mfma_f32_16x16x32_bf16 v[52:55], v[136:139], v[240:243], v[52:55]
	v_mfma_f32_16x16x32_bf16 v[48:51], v[128:131], v[240:243], v[48:51]
	v_mfma_f32_16x16x32_bf16 v[44:47], v[136:139], v[244:247], v[44:47]
	v_mfma_f32_16x16x32_bf16 v[40:43], v[128:131], v[244:247], v[40:43]
	v_mfma_f32_16x16x32_bf16 v[20:23], v[136:139], v[248:251], v[20:23]
	v_mfma_f32_16x16x32_bf16 v[16:19], v[128:131], v[248:251], v[16:19]
	s_cmp_lt_u32 s28, 28
	s_cbranch_scc1 .Lg0_w4_3
	s_waitcnt vmcnt(0)
; #define WAIT_V(n) asm volatile("s_waitcnt vmcnt(" #n ")" ::: "memory")
; #define BAR __builtin_amdgcn_s_barrier()
; #define LDA_(dst, ai) _Pragma("unroll") for (int m = 0; m < 4; ++m) dst[m] = *(const bf16x8*)(sb + (ai) * 8192 + la0 + m * 1024)
; #define LDB_(dst) _Pragma("unroll") for (int bj = 0; bj < 2; ++bj) _Pragma("unroll") for (int n = 0; n < 2; ++n) dst[bj][n] = *(const bf16x8*)(sb + 16384 + bj * 8192 + lb0 + n * 1024)
; #define MMA_(ai, bf_, af_) _Pragma("unroll") for (int bj = 0; bj < 2; ++bj) _Pragma("unroll") for (int m = 0; m < 4; ++m) _Pragma("unroll") for (int n = 0; n < 2; ++n) \
;         acc[ai][bj][m][n] = __builtin_amdgcn_mfma_f32_16x16x32_bf16(bf_[bj][n], af_[m], acc[ai][bj][m][n], 0, 0, 0)
; template <int MODE>
; DI void gemm_phase(const Params& p, int layer, int hf, unsigned char* shmc, int tid) {
;     ...
;     for (int kt = 0; kt < nt; ++kt) {
;       const int rem = nt - 1 - kt;
;       if (rem >= 2) WAIT_V(8); else if (rem == 1) WAIT_V(4); else WAIT_V(0);
;       BAR;
;       const unsigned char* sb = shmc + (kt & 3) * 32768;
;     ...
;       {
;         bf16x8 b0[2][2], a0[4], a1[4];
;         LDB_(b0); LDA_(a0, 0);
;         __builtin_amdgcn_sched_barrier(0);
;         LDA_(a1, 1); MMA_(0, b0, a0);
;         __builtin_amdgcn_sched_barrier(0);
;         if (kt + 3 < nt) STAGE_ALL((kt + 3) & 3, kt + 3);
;         __builtin_amdgcn_sched_barrier(0);
;         MMA_(1, b0, a1);
;       }
;     ...
;     }
.Lg0_w4_3:
	s_waitcnt vmcnt(4)
	s_barrier
	ds_read_b128 v[156:159], v192 offset:40960
	ds_read_b128 v[240:243], v192 offset:41984
	ds_read_b128 v[244:247], v192 offset:43008
	ds_read_b128 v[248:251], v192 offset:44032
	s_waitcnt lgkmcnt(4)
	v_mfma_f32_16x16x32_bf16 v[124:127], v[208:211], v[224:227], v[124:127]
	v_mfma_f32_16x16x32_bf16 v[120:123], v[212:215], v[224:227], v[120:123]
	ds_read_b128 v[140:143], v194 offset:16384
	v_mfma_f32_16x16x32_bf16 v[116:119], v[208:211], v[228:231], v[116:119]
	v_mfma_f32_16x16x32_bf16 v[108:111], v[212:215], v[228:231], v[108:111]
	ds_read_b128 v[144:147], v194 offset:17408
	v_mfma_f32_16x16x32_bf16 v[100:103], v[208:211], v[232:235], v[100:103]
	v_mfma_f32_16x16x32_bf16 v[92:95], v[212:215], v[232:235], v[92:95]
	ds_read_b128 v[136:139], v194 offset:24576
	v_mfma_f32_16x16x32_bf16 v[112:115], v[216:219], v[224:227], v[112:115]
	v_mfma_f32_16x16x32_bf16 v[104:107], v[220:223], v[224:227], v[104:107]
	ds_read_b128 v[128:131], v194 offset:25600
	v_mfma_f32_16x16x32_bf16 v[96:99], v[216:219], v[228:231], v[96:99]
	v_mfma_f32_16x16x32_bf16 v[88:91], v[220:223], v[228:231], v[88:91]
	ds_read_b128 v[132:135], v191
	v_mfma_f32_16x16x32_bf16 v[80:83], v[216:219], v[232:235], v[80:83]
	v_mfma_f32_16x16x32_bf16 v[72:75], v[220:223], v[232:235], v[72:75]
	ds_read_b128 v[148:151], v191 offset:1024
	v_mfma_f32_16x16x32_bf16 v[84:87], v[208:211], v[236:239], v[84:87]
	v_mfma_f32_16x16x32_bf16 v[76:79], v[212:215], v[236:239], v[76:79]
	ds_read_b128 v[152:155], v191 offset:2048
	v_mfma_f32_16x16x32_bf16 v[68:71], v[216:219], v[236:239], v[68:71]
	v_mfma_f32_16x16x32_bf16 v[56:59], v[220:223], v[236:239], v[56:59]
	ds_read_b128 v[204:207], v191 offset:3072
	s_cmp_ge_u32 s28, 28
	s_cbranch_scc1 .Lg0_nost_3
	s_add_u32 m0, s29, 0x10000
	s_add_u32 s18, s98, 0x40000
	s_addc_u32 s19, s99, 0
	global_load_lds_dwordx4 v160, s[98:99]
	s_add_u32 m0, s29, 0x14000
	s_add_u32 s16, s100, 0x40000
	s_addc_u32 s17, s101, 0
	global_load_lds_dwordx4 v160, s[100:101]
	s_add_u32 m0, s29, 0x12000
	s_add_u32 s98, s98, 0x2000
	s_addc_u32 s99, s99, 0
	global_load_lds_dwordx4 v160, s[18:19]
	s_add_u32 m0, s29, 0x16000
	s_add_u32 s100, s100, 0x2000
	s_addc_u32 s101, s101, 0
	global_load_lds_dwordx4 v160, s[16:17]
.Lg0_nost_3:
	s_waitcnt lgkmcnt(8)
	v_mfma_f32_16x16x32_bf16 v[36:39], v[208:211], v[156:159], v[36:39]
	v_mfma_f32_16x16x32_bf16 v[24:27], v[212:215], v[156:159], v[24:27]
	v_mfma_f32_16x16x32_bf16 v[4:7], v[208:211], v[240:243], v[4:7]
	v_mfma_f32_16x16x32_bf16 v[0:3], v[212:215], v[240:243], v[0:3]
	v_mfma_f32_16x16x32_bf16 v[32:35], v[208:211], v[244:247], v[32:35]
	v_mfma_f32_16x16x32_bf16 v[28:31], v[212:215], v[244:247], v[28:31]
	v_mfma_f32_16x16x32_bf16 v[12:15], v[208:211], v[248:251], v[12:15]
	v_mfma_f32_16x16x32_bf16 v[8:11], v[212:215], v[248:251], v[8:11]
	v_mfma_f32_16x16x32_bf16 v[64:67], v[216:219], v[156:159], v[64:67]
	v_mfma_f32_16x16x32_bf16 v[60:63], v[220:223], v[156:159], v[60:63]
	v_mfma_f32_16x16x32_bf16 v[52:55], v[216:219], v[240:243], v[52:55]
	v_mfma_f32_16x16x32_bf16 v[48:51], v[220:223], v[240:243], v[48:51]
	v_mfma_f32_16x16x32_bf16 v[44:47], v[216:219], v[244:247], v[44:47]
	v_mfma_f32_16x16x32_bf16 v[40:43], v[220:223], v[244:247], v[40:43]
	v_mfma_f32_16x16x32_bf16 v[20:23], v[216:219], v[248:251], v[20:23]
	v_mfma_f32_16x16x32_bf16 v[16:19], v[220:223], v[248:251], v[16:19]
	s_add_i32 s28, s28, 4
	s_cmp_lt_u32 s28, 32
	s_cbranch_scc1 .Lg0_loop
	s_waitcnt lgkmcnt(0)

; DI void unpack8(uint4 v, float* f) { f[0] = bflo(v.x); f[1] = bfhi(v.x); f[2] = bflo(v.y); f[3] = bfhi(v.y); f[4] = bflo(v.z); f[5] = bfhi(v.z); f[6] = bflo(v.w); f[7] = bfhi(v.w); }
; DI uint4 pack8(const float* f) { uint4 r; r.x = pk2(f[0], f[1]); r.y = pk2(f[2], f[3]); r.z = pk2(f[4], f[5]); r.w = pk2(f[6], f[7]); return r; }
; DI float ex2(float x) { return __builtin_amdgcn_exp2f(x); }
; DI void ret_out_unit(const Params& p, int hf, int bl, int c, int hd, unsigned char* shm, int tid, bool dry = false) {
;     ...
;   const float lg = logf(1.0f - ex2(-5.0f - (float)hd));
; #pragma unroll
;   for (int it = 0; it < 2; ++it) {
;     const int idx = tid + it * NTHR, j = idx >> 3, dg = idx & 7;
;     const bf16_t* base = projb + (size_t)(c * 128 + j) * NP;
;     float q1[8], q2[8], k1[8], k2[8];
;     unpack8(*(const uint4*)(base + C_RQ + hd * 128 + dg * 8), q1); unpack8(*(const uint4*)(base + C_RQ + hd * 128 + 64 + dg * 8), q2);
;     unpack8(*(const uint4*)(base + C_RK + hd * 128 + dg * 8), k1); unpack8(*(const uint4*)(base + C_RK + hd * 128 + 64 + dg * 8), k2);
;     float oq1[8], oq2[8], ok1[8], ok2[8];
; #pragma unroll
;     for (int e = 0; e < 8; ++e) {
;       const float2 t = cs[j * 64 + dg * 8 + e];
;       oq1[e] = q1[e] * t.x - q2[e] * t.y; oq2[e] = q1[e] * t.y + q2[e] * t.x;
;       ok1[e] = (k1[e] * t.x - k2[e] * t.y) * 0.08838834764831845f; ok2[e] = (k1[e] * t.y + k2[e] * t.x) * 0.08838834764831845f;
;     }
;     *(uint4*)(sQ + j * LD + dg * 8) = pack8(oq1); *(uint4*)(sQ + j * LD + 64 + dg * 8) = pack8(oq2);
;     *(uint4*)(sK + j * LD + dg * 8) = pack8(ok1); *(uint4*)(sK + j * LD + 64 + dg * 8) = pack8(ok2);
;     *(uint4*)(sVt + j * LD + dg * 16) = *(const uint4*)(base + C_RV + hd * 128 + dg * 16);
;     *(uint4*)(sVt + j * LD + dg * 16 + 8) = *(const uint4*)(base + C_RV + hd * 128 + dg * 16 + 8);
.LBB0_431:
	v_writelane_b32 v254, s4, 61
	s_nop 1
	v_writelane_b32 v254, s5, 62
	s_nop 0
	v_readlane_b32 s0, v254, 60
	s_cmpk_gt_i32 s0, 0xff
	s_mov_b64 s[0:1], -1
	s_cbranch_scc0 .LBB0_588
	v_readlane_b32 s0, v254, 60
	s_cmpk_gt_u32 s0, 0x1bf
	s_mov_b64 s[0:1], -1
	s_cbranch_scc0 .LBB0_573
	v_readlane_b32 s0, v254, 60
	s_cmpk_gt_i32 s0, 0x23f
	s_mov_b64 s[0:1], -1
	s_cbranch_scc0 .LBB0_500
	v_readlane_b32 s0, v254, 60
	s_cmpk_gt_u32 s0, 0x33f
	s_mov_b64 s[0:1], -1
	s_cbranch_scc0 .LBB0_468
	v_readlane_b32 s0, v254, 60
	s_add_i32 s5, s0, 0xfffffcc0
	s_lshr_b32 s4, s5, 8
	s_mul_i32 s2, s4, 0x3400000
	s_bfe_u32 s7, s5, 0x60002
	s_and_b32 s6, s23, 3
	s_lshl_b64 s[0:1], s[2:3], 1
	s_add_u32 s8, s38, s0
	v_cvt_f32_ubyte0_e32 v0, s6
	s_addc_u32 s9, s39, s1
	s_lshl_b32 s0, s4, 13
	v_sub_f32_e32 v0, 0xc0a00000, v0
	s_add_i32 s0, s0, s68
	s_lshl_b32 s4, s7, 7
	v_exp_f32_e32 v0, v0
	s_or_b32 s0, s0, s4
	s_lshl_b32 s2, s0, 6
	v_mov_b32_e32 v66, v163
	s_lshl_b64 s[0:1], s[2:3], 3
	v_readlane_b32 s2, v252, 45
	s_add_u32 s0, s2, s0
	v_readlane_b32 s2, v252, 46
	v_sub_f32_e32 v32, 1.0, v0
	v_and_b32_e32 v0, 7, v66
	v_ashrrev_i32_e32 v18, 3, v66
	s_addc_u32 s1, s2, s1
	v_lshlrev_b32_e32 v20, 3, v0
	v_lshlrev_b32_e32 v160, 4, v0
	v_lshlrev_b32_e32 v12, 5, v0
	v_readlane_b32 s2, v254, 0
	v_add_u32_e32 v0, s4, v18
	v_mov_b64_e32 v[16:17], s[8:9]
	v_add_u32_e32 v19, s2, v12
	v_mad_i64_i32 v[0:1], s[8:9], v0, s65, v[16:17]
	s_lshl_b32 s2, s6, 8
	v_lshl_add_u64 v[14:15], v[0:1], 0, s[2:3]
	v_lshl_add_u64 v[4:5], v[14:15], 0, v[160:161]
	v_lshl_add_u64 v[224:225], v[14:15], 0, v[160:161]
	global_load_dwordx4 v[100:103], v[224:225], off
	global_load_dwordx4 v[104:107], v[224:225], off offset:128
	global_load_dwordx4 v[108:111], v[224:225], off offset:1024
	global_load_dwordx4 v[112:115], v[224:225], off offset:1152
	v_lshl_or_b32 v226, v18, 6, v20
	v_mov_b32_e32 v227, v161
	v_lshl_add_u64 v[226:227], v[226:227], 3, s[0:1]
	global_load_dwordx4 v[116:119], v[226:227], off offset:48
	global_load_dwordx4 v[120:123], v[226:227], off offset:32
	global_load_dwordx4 v[124:127], v[226:227], off offset:16
	global_load_dwordx4 v[128:131], v[226:227], off
	v_mov_b32_e32 v228, v12
	v_mov_b32_e32 v229, v161
	v_lshl_add_u64 v[228:229], v[14:15], 0, v[228:229]
	global_load_dwordx4 v[132:135], v[228:229], off offset:2048
	global_load_dwordx4 v[136:139], v[228:229], off offset:2064
	v_add_u32_e32 v230, 64, v18
	v_add_u32_e32 v231, s4, v230
	v_mad_i64_i32 v[232:233], s[8:9], v231, s65, v[16:17]
	v_lshl_add_u64 v[232:233], v[232:233], 0, s[2:3]
	v_lshl_add_u64 v[234:235], v[232:233], 0, v[160:161]
	global_load_dwordx4 v[140:143], v[234:235], off
	global_load_dwordx4 v[144:147], v[234:235], off offset:128
	global_load_dwordx4 v[148:151], v[234:235], off offset:1024
	global_load_dwordx4 v[152:155], v[234:235], off offset:1152
	v_lshl_or_b32 v236, v230, 6, v20
	v_mov_b32_e32 v237, v161
	v_lshl_add_u64 v[236:237], v[236:237], 3, s[0:1]
	global_load_dwordx4 v[156:159], v[236:237], off offset:48
	global_load_dwordx4 v[204:207], v[236:237], off offset:32
	global_load_dwordx4 v[208:211], v[236:237], off offset:16
	global_load_dwordx4 v[212:215], v[236:237], off
	v_mov_b32_e32 v238, v12
	v_mov_b32_e32 v239, v161
	v_lshl_add_u64 v[238:239], v[232:233], 0, v[238:239]
	global_load_dwordx4 v[216:219], v[238:239], off offset:2048
	global_load_dwordx4 v[220:223], v[238:239], off offset:2064
	v_mul_lo_u32 v67, v18, s66
	v_ashrrev_i32_e32 v73, 6, v66
	v_and_b32_e32 v74, 15, v66
	v_lshl_or_b32 v68, v73, 4, v74
	v_bfe_u32 v75, v66, 4, 2
	v_mul_u32_u24_e32 v71, 0x110, v74
	s_waitcnt vmcnt(19)
	v_mov_b32_e32 v0, v100
	v_mov_b32_e32 v1, v101
	v_mov_b32_e32 v2, v102
	v_mov_b32_e32 v3, v103
	v_lshlrev_b32_e32 v26, 16, v0
	v_and_b32_e32 v27, 0xffff0000, v0
	v_lshlrev_b32_e32 v28, 16, v1
	v_and_b32_e32 v29, 0xffff0000, v1
	v_lshlrev_b32_e32 v30, 16, v2
	v_and_b32_e32 v31, 0xffff0000, v2
	v_lshlrev_b32_e32 v21, 16, v3
	v_and_b32_e32 v13, 0xffff0000, v3
	s_waitcnt vmcnt(18)
	v_mov_b32_e32 v0, v104
	v_mov_b32_e32 v1, v105
	v_mov_b32_e32 v2, v106
	v_mov_b32_e32 v3, v107
	v_lshlrev_b32_e32 v33, 16, v0
	v_and_b32_e32 v34, 0xffff0000, v0
	v_lshlrev_b32_e32 v35, 16, v1
	v_and_b32_e32 v36, 0xffff0000, v1
	v_lshlrev_b32_e32 v37, 16, v2
	v_and_b32_e32 v38, 0xffff0000, v2
	v_lshlrev_b32_e32 v39, 16, v3
	v_and_b32_e32 v40, 0xffff0000, v3
	s_waitcnt vmcnt(17)
	v_mov_b32_e32 v0, v108
	v_mov_b32_e32 v1, v109
	v_mov_b32_e32 v2, v110
	v_mov_b32_e32 v3, v111
	v_lshlrev_b32_e32 v41, 16, v0
	v_and_b32_e32 v42, 0xffff0000, v0
	v_lshlrev_b32_e32 v43, 16, v1
	v_and_b32_e32 v44, 0xffff0000, v1
	v_lshlrev_b32_e32 v45, 16, v2
	v_and_b32_e32 v46, 0xffff0000, v2
	v_lshlrev_b32_e32 v47, 16, v3
	v_and_b32_e32 v48, 0xffff0000, v3
	s_waitcnt vmcnt(16)
	v_mov_b32_e32 v0, v112
	v_mov_b32_e32 v1, v113
	v_mov_b32_e32 v2, v114
	v_mov_b32_e32 v3, v115
	v_lshlrev_b32_e32 v49, 16, v0
	v_and_b32_e32 v50, 0xffff0000, v0
	v_lshl_or_b32 v0, v18, 6, v20
	v_lshlrev_b32_e32 v51, 16, v1
	v_and_b32_e32 v52, 0xffff0000, v1
	v_ashrrev_i32_e32 v1, 31, v0
	v_lshl_add_u64 v[22:23], v[0:1], 3, s[0:1]
	v_lshlrev_b32_e32 v53, 16, v2
	v_and_b32_e32 v54, 0xffff0000, v2
	v_lshlrev_b32_e32 v55, 16, v3
	v_and_b32_e32 v56, 0xffff0000, v3
	s_nop 0
	s_waitcnt vmcnt(12)
; DI void unpack8(uint4 v, float* f) { f[0] = bflo(v.x); f[1] = bfhi(v.x); f[2] = bflo(v.y); f[3] = bfhi(v.y); f[4] = bflo(v.z); f[5] = bfhi(v.z); f[6] = bflo(v.w); f[7] = bfhi(v.w); }
; DI uint4 pack8(const float* f) { uint4 r; r.x = pk2(f[0], f[1]); r.y = pk2(f[2], f[3]); r.z = pk2(f[4], f[5]); r.w = pk2(f[6], f[7]); return r; }
; DI void ret_out_unit(const Params& p, int hf, int bl, int c, int hd, unsigned char* shm, int tid, bool dry = false) {
;     ...
;   for (int it = 0; it < 2; ++it) {
;     const int idx = tid + it * NTHR, j = idx >> 3, dg = idx & 7;
;     const bf16_t* base = projb + (size_t)(c * 128 + j) * NP;
;     float q1[8], q2[8], k1[8], k2[8];
;     unpack8(*(const uint4*)(base + C_RQ + hd * 128 + dg * 8), q1); unpack8(*(const uint4*)(base + C_RQ + hd * 128 + 64 + dg * 8), q2);
;     unpack8(*(const uint4*)(base + C_RK + hd * 128 + dg * 8), k1); unpack8(*(const uint4*)(base + C_RK + hd * 128 + 64 + dg * 8), k2);
;     float oq1[8], oq2[8], ok1[8], ok2[8];
; #pragma unroll
;     for (int e = 0; e < 8; ++e) {
;       const float2 t = cs[j * 64 + dg * 8 + e];
;       oq1[e] = q1[e] * t.x - q2[e] * t.y; oq2[e] = q1[e] * t.y + q2[e] * t.x;
;       ok1[e] = (k1[e] * t.x - k2[e] * t.y) * 0.08838834764831845f; ok2[e] = (k1[e] * t.y + k2[e] * t.x) * 0.08838834764831845f;
;     }
;     *(uint4*)(sQ + j * LD + dg * 8) = pack8(oq1); *(uint4*)(sQ + j * LD + 64 + dg * 8) = pack8(oq2);
;     *(uint4*)(sK + j * LD + dg * 8) = pack8(ok1); *(uint4*)(sK + j * LD + 64 + dg * 8) = pack8(ok2);
;     *(uint4*)(sVt + j * LD + dg * 16) = *(const uint4*)(base + C_RV + hd * 128 + dg * 16);
;     *(uint4*)(sVt + j * LD + dg * 16 + 8) = *(const uint4*)(base + C_RV + hd * 128 + dg * 16 + 8);
	v_mov_b32_e32 v0, v116
	v_mov_b32_e32 v1, v117
	v_mov_b32_e32 v2, v118
	v_mov_b32_e32 v3, v119
	v_mov_b32_e32 v4, v120
	v_mov_b32_e32 v5, v121
	v_mov_b32_e32 v6, v122
	v_mov_b32_e32 v7, v123
	v_mov_b32_e32 v8, v124
	v_mov_b32_e32 v9, v125
	v_mov_b32_e32 v10, v126
	v_mov_b32_e32 v11, v127
	v_mov_b32_e32 v22, v128
	v_mov_b32_e32 v23, v129
	v_mov_b32_e32 v24, v130
	v_mov_b32_e32 v25, v131
	v_mul_f32_e32 v57, v23, v33
	v_fma_f32 v57, v22, v26, -v57
	v_mul_f32_e32 v26, v23, v26
	v_fmac_f32_e32 v26, v22, v33
	v_mul_f32_e32 v33, v23, v49
	v_mul_f32_e32 v23, v23, v41
	v_fmac_f32_e32 v23, v22, v49
	v_fma_f32 v33, v22, v41, -v33
	v_mul_f32_e32 v22, 0x3db504f3, v23
	v_mul_f32_e32 v23, v25, v34
	v_fma_f32 v23, v24, v27, -v23
	v_mul_f32_e32 v27, v25, v27
	v_fmac_f32_e32 v27, v24, v34
	v_mul_f32_e32 v34, v25, v50
	v_mul_f32_e32 v25, v25, v42
	v_fmac_f32_e32 v25, v24, v50
	v_fma_f32 v34, v24, v42, -v34
	v_mul_f32_e32 v24, 0x3db504f3, v25
	v_mul_f32_e32 v25, v9, v35
	v_fma_f32 v25, v8, v28, -v25
	v_mul_f32_e32 v28, v9, v28
	v_fmac_f32_e32 v28, v8, v35
	v_mul_f32_e32 v35, v9, v51
	v_mul_f32_e32 v9, v9, v43
	v_fmac_f32_e32 v9, v8, v51
	v_fma_f32 v35, v8, v43, -v35
	v_mul_f32_e32 v8, 0x3db504f3, v9
	v_mul_f32_e32 v9, v11, v36
	v_fma_f32 v9, v10, v29, -v9
	v_mul_f32_e32 v29, v11, v29
	v_fmac_f32_e32 v29, v10, v36
	v_mul_f32_e32 v36, v11, v52
	v_mul_f32_e32 v11, v11, v44
	v_fmac_f32_e32 v11, v10, v52
	v_fma_f32 v36, v10, v44, -v36
	v_mul_f32_e32 v10, 0x3db504f3, v11
	v_mul_f32_e32 v11, v5, v37
	v_fma_f32 v11, v4, v30, -v11
	v_mul_f32_e32 v30, v5, v30
	v_fmac_f32_e32 v30, v4, v37
	v_mul_f32_e32 v37, v5, v53
	v_mul_f32_e32 v5, v5, v45
	v_fmac_f32_e32 v5, v4, v53
	v_fma_f32 v37, v4, v45, -v37
	v_mul_f32_e32 v4, 0x3db504f3, v5
	v_mul_f32_e32 v5, v7, v38
	v_fma_f32 v5, v6, v31, -v5
	v_mul_f32_e32 v31, v7, v31
	v_fmac_f32_e32 v31, v6, v38
	v_mul_f32_e32 v38, v7, v54
	v_mul_f32_e32 v7, v7, v46
	v_fmac_f32_e32 v7, v6, v54
	v_fma_f32 v38, v6, v46, -v38
	v_mul_f32_e32 v6, 0x3db504f3, v7
	v_mul_f32_e32 v7, v1, v39
	v_fma_f32 v7, v0, v21, -v7
	v_mul_f32_e32 v21, v1, v21
	v_fmac_f32_e32 v21, v0, v39
	v_mul_f32_e32 v39, v1, v55
	v_mul_f32_e32 v1, v1, v47
	v_fma_f32 v39, v0, v47, -v39
	v_fmac_f32_e32 v1, v0, v55
	v_mul_f32_e32 v0, v3, v40
	v_fma_f32 v42, v2, v13, -v0
	v_mul_f32_e32 v0, v3, v56
	v_mul_f32_e32 v13, v3, v13
	v_fma_f32 v0, v2, v48, -v0
	v_fmac_f32_e32 v13, v2, v40
	v_mul_f32_e32 v40, 0x3db504f3, v0
	v_mul_f32_e32 v0, v3, v48
	v_fmac_f32_e32 v0, v2, v56
	v_mul_f32_e32 v41, 0x3db504f3, v1
	v_mul_f32_e32 v43, 0x3db504f3, v0
	v_cvt_pk_bf16_f32 v0, v57, v23
	v_cvt_pk_bf16_f32 v1, v25, v9
	v_cvt_pk_bf16_f32 v2, v11, v5
	v_cvt_pk_bf16_f32 v3, v7, v42
	v_add3_u32 v5, 32, v67, v160
	ds_write_b128 v5, v[0:3]
	v_cvt_pk_bf16_f32 v0, v26, v27
	v_cvt_pk_bf16_f32 v1, v28, v29
	v_cvt_pk_bf16_f32 v2, v30, v31
	v_cvt_pk_bf16_f32 v3, v21, v13
	v_mul_f32_e32 v33, 0x3db504f3, v33
	v_mul_f32_e32 v34, 0x3db504f3, v34
	v_mul_f32_e32 v35, 0x3db504f3, v35
	v_mul_f32_e32 v36, 0x3db504f3, v36
	v_mul_f32_e32 v37, 0x3db504f3, v37
	v_mul_f32_e32 v38, 0x3db504f3, v38
	v_mul_f32_e32 v39, 0x3db504f3, v39
	ds_write_b128 v5, v[0:3] offset:128
	v_cvt_pk_bf16_f32 v0, v33, v34
	v_cvt_pk_bf16_f32 v1, v35, v36
	v_cvt_pk_bf16_f32 v2, v37, v38
	v_cvt_pk_bf16_f32 v3, v39, v40
	v_mov_b32_e32 v13, v161
	ds_write_b128 v5, v[0:3] offset:34816
	v_cvt_pk_bf16_f32 v0, v22, v24
	v_cvt_pk_bf16_f32 v1, v8, v10
	v_cvt_pk_bf16_f32 v2, v4, v6
	v_cvt_pk_bf16_f32 v3, v41, v43
	ds_write_b128 v5, v[0:3] offset:34944
	v_lshl_add_u64 v[4:5], v[14:15], 0, v[12:13]
	v_add_u32_e32 v6, v19, v67
	s_waitcnt vmcnt(11)
	v_mov_b32_e32 v0, v132
	v_mov_b32_e32 v1, v133
	v_mov_b32_e32 v2, v134
	v_mov_b32_e32 v3, v135
	ds_write_b128 v6, v[0:3]
	s_waitcnt vmcnt(10)
	v_mov_b32_e32 v0, v136
	v_mov_b32_e32 v1, v137
	v_mov_b32_e32 v2, v138
	v_mov_b32_e32 v3, v139
	ds_write_b128 v6, v[0:3] offset:16
	v_add_u32_e32 v0, 0x200, v66
	v_ashrrev_i32_e32 v14, 3, v0
	v_add_u32_e32 v0, s4, v14
	v_mad_i64_i32 v[0:1], s[8:9], v0, s65, v[16:17]
	v_lshl_add_u64 v[4:5], v[0:1], 0, s[2:3]
	v_lshl_add_u64 v[6:7], v[4:5], 0, v[160:161]
	v_lshl_add_u64 v[4:5], v[4:5], 0, v[12:13]
	s_waitcnt vmcnt(9)
	v_mov_b32_e32 v0, v140
	v_mov_b32_e32 v1, v141
	v_mov_b32_e32 v2, v142
	v_mov_b32_e32 v3, v143
	v_lshlrev_b32_e32 v15, 16, v0
	v_and_b32_e32 v28, 0xffff0000, v0
	v_lshlrev_b32_e32 v29, 16, v1
	v_and_b32_e32 v30, 0xffff0000, v1
	v_lshlrev_b32_e32 v31, 16, v2
	v_and_b32_e32 v33, 0xffff0000, v2
	v_lshlrev_b32_e32 v34, 16, v3
	v_and_b32_e32 v35, 0xffff0000, v3
	s_waitcnt vmcnt(8)
	v_mov_b32_e32 v0, v144
	v_mov_b32_e32 v1, v145
	v_mov_b32_e32 v2, v146
	v_mov_b32_e32 v3, v147
	v_lshlrev_b32_e32 v36, 16, v0
	v_and_b32_e32 v37, 0xffff0000, v0
	v_lshlrev_b32_e32 v38, 16, v1
	v_and_b32_e32 v39, 0xffff0000, v1
	v_lshlrev_b32_e32 v40, 16, v2
	v_and_b32_e32 v41, 0xffff0000, v2
	v_lshlrev_b32_e32 v42, 16, v3
	v_and_b32_e32 v43, 0xffff0000, v3
	s_waitcnt vmcnt(7)
	v_mov_b32_e32 v0, v148
	v_mov_b32_e32 v1, v149
	v_mov_b32_e32 v2, v150
	v_mov_b32_e32 v3, v151
	v_lshlrev_b32_e32 v44, 16, v0
	v_and_b32_e32 v45, 0xffff0000, v0
	v_lshlrev_b32_e32 v46, 16, v1
	v_and_b32_e32 v47, 0xffff0000, v1
	v_lshlrev_b32_e32 v48, 16, v2
	v_and_b32_e32 v49, 0xffff0000, v2
	v_lshlrev_b32_e32 v50, 16, v3
	v_and_b32_e32 v51, 0xffff0000, v3
	s_waitcnt vmcnt(6)
; DI void unpack8(uint4 v, float* f) { f[0] = bflo(v.x); f[1] = bfhi(v.x); f[2] = bflo(v.y); f[3] = bfhi(v.y); f[4] = bflo(v.z); f[5] = bfhi(v.z); f[6] = bflo(v.w); f[7] = bfhi(v.w); }
; DI uint4 pack8(const float* f) { uint4 r; r.x = pk2(f[0], f[1]); r.y = pk2(f[2], f[3]); r.z = pk2(f[4], f[5]); r.w = pk2(f[6], f[7]); return r; }
; DI void ret_out_unit(const Params& p, int hf, int bl, int c, int hd, unsigned char* shm, int tid, bool dry = false) {
;     ...
;   for (int it = 0; it < 2; ++it) {
;     const int idx = tid + it * NTHR, j = idx >> 3, dg = idx & 7;
;     const bf16_t* base = projb + (size_t)(c * 128 + j) * NP;
;     float q1[8], q2[8], k1[8], k2[8];
;     unpack8(*(const uint4*)(base + C_RQ + hd * 128 + dg * 8), q1); unpack8(*(const uint4*)(base + C_RQ + hd * 128 + 64 + dg * 8), q2);
;     unpack8(*(const uint4*)(base + C_RK + hd * 128 + dg * 8), k1); unpack8(*(const uint4*)(base + C_RK + hd * 128 + 64 + dg * 8), k2);
;     float oq1[8], oq2[8], ok1[8], ok2[8];
; #pragma unroll
;     for (int e = 0; e < 8; ++e) {
;       const float2 t = cs[j * 64 + dg * 8 + e];
;       oq1[e] = q1[e] * t.x - q2[e] * t.y; oq2[e] = q1[e] * t.y + q2[e] * t.x;
;       ok1[e] = (k1[e] * t.x - k2[e] * t.y) * 0.08838834764831845f; ok2[e] = (k1[e] * t.y + k2[e] * t.x) * 0.08838834764831845f;
;     }
;     *(uint4*)(sQ + j * LD + dg * 8) = pack8(oq1); *(uint4*)(sQ + j * LD + 64 + dg * 8) = pack8(oq2);
;     *(uint4*)(sK + j * LD + dg * 8) = pack8(ok1); *(uint4*)(sK + j * LD + 64 + dg * 8) = pack8(ok2);
;     *(uint4*)(sVt + j * LD + dg * 16) = *(const uint4*)(base + C_RV + hd * 128 + dg * 16);
;     *(uint4*)(sVt + j * LD + dg * 16 + 8) = *(const uint4*)(base + C_RV + hd * 128 + dg * 16 + 8);
	v_mov_b32_e32 v0, v152
	v_mov_b32_e32 v1, v153
	v_mov_b32_e32 v2, v154
	v_mov_b32_e32 v3, v155
	v_lshlrev_b32_e32 v52, 16, v0
	v_and_b32_e32 v53, 0xffff0000, v0
	v_lshl_or_b32 v0, v14, 6, v20
	v_lshlrev_b32_e32 v54, 16, v1
	v_and_b32_e32 v55, 0xffff0000, v1
	v_ashrrev_i32_e32 v1, 31, v0
	v_lshl_add_u64 v[10:11], v[0:1], 3, s[0:1]
	v_lshlrev_b32_e32 v56, 16, v2
	v_and_b32_e32 v57, 0xffff0000, v2
	v_lshlrev_b32_e32 v58, 16, v3
	v_and_b32_e32 v59, 0xffff0000, v3
	s_and_b32 s0, s5, 0x3ff00
	s_lshl_b32 s1, s7, 2
	s_or_b32 s0, s1, s0
	s_or_b32 s0, s0, s6
	s_lshl_b32 s0, s0, 14
	s_mov_b32 s1, s3
	s_lshl_b64 s[0:1], s[0:1], 1
	v_readlane_b32 s5, v253, 28
	s_add_u32 s0, s5, s0
	v_readlane_b32 s5, v253, 29
	s_addc_u32 s1, s5, s1
	s_waitcnt vmcnt(2)
	v_mov_b32_e32 v0, v156
	v_mov_b32_e32 v1, v157
	v_mov_b32_e32 v2, v158
	v_mov_b32_e32 v3, v159
	v_mov_b32_e32 v6, v204
	v_mov_b32_e32 v7, v205
	v_mov_b32_e32 v8, v206
	v_mov_b32_e32 v9, v207
	v_mov_b32_e32 v20, v208
	v_mov_b32_e32 v21, v209
	v_mov_b32_e32 v22, v210
	v_mov_b32_e32 v23, v211
	v_mov_b32_e32 v24, v212
	v_mov_b32_e32 v25, v213
	v_mov_b32_e32 v26, v214
	v_mov_b32_e32 v27, v215
	v_mul_f32_e32 v10, v25, v36
	v_fma_f32 v10, v24, v15, -v10
	v_mul_f32_e32 v11, v25, v15
	v_mul_f32_e32 v15, v25, v52
	v_mul_f32_e32 v25, v25, v44
	v_fmac_f32_e32 v25, v24, v52
	v_fmac_f32_e32 v11, v24, v36
	v_fma_f32 v15, v24, v44, -v15
	v_mul_f32_e32 v24, 0x3db504f3, v25
	v_mul_f32_e32 v25, v27, v37
	v_fma_f32 v25, v26, v28, -v25
	v_mul_f32_e32 v28, v27, v28
	v_mul_f32_e32 v36, v27, v53
	v_mul_f32_e32 v27, v27, v45
	v_fmac_f32_e32 v27, v26, v53
	v_fmac_f32_e32 v28, v26, v37
	v_fma_f32 v36, v26, v45, -v36
	v_mul_f32_e32 v26, 0x3db504f3, v27
	v_mul_f32_e32 v27, v21, v38
	v_fma_f32 v27, v20, v29, -v27
	v_mul_f32_e32 v29, v21, v29
	v_mul_f32_e32 v37, v21, v54
	v_mul_f32_e32 v21, v21, v46
	v_fmac_f32_e32 v21, v20, v54
	v_fmac_f32_e32 v29, v20, v38
	v_fma_f32 v37, v20, v46, -v37
	v_mul_f32_e32 v20, 0x3db504f3, v21
	v_mul_f32_e32 v21, v23, v39
	v_fma_f32 v21, v22, v30, -v21
	v_mul_f32_e32 v30, v23, v30
	v_mul_f32_e32 v38, v23, v55
	v_mul_f32_e32 v23, v23, v47
	v_fmac_f32_e32 v23, v22, v55
	v_fmac_f32_e32 v30, v22, v39
	v_fma_f32 v38, v22, v47, -v38
	v_mul_f32_e32 v22, 0x3db504f3, v23
	v_mul_f32_e32 v23, v7, v40
	v_fma_f32 v23, v6, v31, -v23
	v_mul_f32_e32 v31, v7, v31
	v_mul_f32_e32 v39, v7, v56
	v_mul_f32_e32 v7, v7, v48
	v_fmac_f32_e32 v7, v6, v56
	v_fmac_f32_e32 v31, v6, v40
	v_fma_f32 v39, v6, v48, -v39
	v_mul_f32_e32 v6, 0x3db504f3, v7
	v_mul_f32_e32 v7, v9, v41
	v_fma_f32 v7, v8, v33, -v7
	v_mul_f32_e32 v33, v9, v33
	v_mul_f32_e32 v40, v9, v57
	v_mul_f32_e32 v9, v9, v49
	v_fmac_f32_e32 v9, v8, v57
	v_fmac_f32_e32 v33, v8, v41
	v_fma_f32 v40, v8, v49, -v40
	v_mul_f32_e32 v8, 0x3db504f3, v9
	v_mul_f32_e32 v9, v1, v42
	v_fma_f32 v9, v0, v34, -v9
	v_mul_f32_e32 v34, v1, v34
	v_mul_f32_e32 v41, v1, v58
	v_mul_f32_e32 v1, v1, v50
	v_fmac_f32_e32 v34, v0, v42
	v_fma_f32 v41, v0, v50, -v41
	v_fmac_f32_e32 v1, v0, v58
	v_mul_f32_e32 v0, v3, v43
	v_fma_f32 v44, v2, v35, -v0
	v_mul_f32_e32 v0, v3, v59
	v_mul_f32_e32 v35, v3, v35
	v_fma_f32 v0, v2, v51, -v0
	v_fmac_f32_e32 v35, v2, v43
	v_mul_f32_e32 v43, 0x3db504f3, v0
	v_mul_f32_e32 v0, v3, v51
	v_fmac_f32_e32 v0, v2, v59
	v_mul_f32_e32 v42, 0x3db504f3, v1
	v_mul_f32_e32 v45, 0x3db504f3, v0
	v_cvt_pk_bf16_f32 v0, v10, v25
	v_cvt_pk_bf16_f32 v1, v27, v21
	v_cvt_pk_bf16_f32 v2, v23, v7
	v_mul_lo_u32 v7, v14, s66
	v_cvt_pk_bf16_f32 v3, v9, v44
	v_add3_u32 v9, 32, v7, v160
	ds_write_b128 v9, v[0:3]
	v_cvt_pk_bf16_f32 v0, v11, v28
	v_cvt_pk_bf16_f32 v1, v29, v30
	v_cvt_pk_bf16_f32 v2, v31, v33
	v_cvt_pk_bf16_f32 v3, v34, v35
	v_mul_f32_e32 v15, 0x3db504f3, v15
	v_mul_f32_e32 v36, 0x3db504f3, v36
	v_mul_f32_e32 v37, 0x3db504f3, v37
	v_mul_f32_e32 v38, 0x3db504f3, v38
	v_mul_f32_e32 v39, 0x3db504f3, v39
	v_mul_f32_e32 v40, 0x3db504f3, v40
	v_mul_f32_e32 v41, 0x3db504f3, v41
	ds_write_b128 v9, v[0:3] offset:128
	v_cvt_pk_bf16_f32 v0, v15, v36
	v_cvt_pk_bf16_f32 v1, v37, v38
	v_cvt_pk_bf16_f32 v2, v39, v40
	v_cvt_pk_bf16_f32 v3, v41, v43
	ds_write_b128 v9, v[0:3] offset:34816
	v_cvt_pk_bf16_f32 v0, v24, v26
	v_cvt_pk_bf16_f32 v1, v20, v22
	v_cvt_pk_bf16_f32 v2, v6, v8
	v_cvt_pk_bf16_f32 v3, v42, v45
	ds_write_b128 v9, v[0:3] offset:34944
	v_add_u32_e32 v6, v19, v7
	v_lshlrev_b32_e32 v8, 7, v18
	v_ashrrev_i32_e32 v9, 31, v8
	v_add_u32_e32 v18, s4, v68
	v_lshlrev_b32_e32 v34, 3, v75
	v_mov_b32_e32 v35, v161
	v_mul_lo_u32 v33, v68, s66
	v_add_u32_e32 v70, 32, v33
	v_lshlrev_b32_e32 v36, 2, v75
	s_waitcnt vmcnt(1)
	v_mov_b32_e32 v0, v216
	v_mov_b32_e32 v1, v217
	v_mov_b32_e32 v2, v218
	v_mov_b32_e32 v3, v219
	ds_write_b128 v6, v[0:3]
	s_waitcnt vmcnt(0)
	v_mov_b32_e32 v0, v220
	v_mov_b32_e32 v1, v221
	v_mov_b32_e32 v2, v222
	v_mov_b32_e32 v3, v223
	ds_write_b128 v6, v[0:3] offset:16
	v_lshl_add_u64 v[0:1], v[8:9], 1, s[0:1]
	v_add_u32_e32 v8, 0x2000, v8
	v_ashrrev_i32_e32 v9, 31, v8
	v_lshl_add_u64 v[8:9], v[8:9], 1, s[0:1]
	v_mad_i64_i32 v[16:17], s[0:1], v18, s65, v[16:17]
	v_lshl_add_u64 v[16:17], v[16:17], 0, s[2:3]
	v_lshlrev_b32_e32 v2, 4, v66
	v_lshl_add_u64 v[16:17], v[16:17], 0, v[34:35]
	s_mov_b64 s[0:1], 0x2400
	v_and_b32_e32 v2, 0x70, v2
	v_lshl_add_u64 v[48:49], v[16:17], 0, s[0:1]
	s_movk_i32 s0, 0x2000
	v_lshlrev_b32_e32 v160, 1, v2
	v_add_co_u32_e32 v16, vcc, s0, v16
	v_lshl_add_u64 v[4:5], v[0:1], 0, v[160:161]
	v_lshl_add_u64 v[12:13], v[8:9], 0, v[160:161]
	v_addc_co_u32_e32 v17, vcc, 0, v17, vcc
	s_waitcnt lgkmcnt(0)
	s_barrier
; DI unsigned pk2(float lo, float hi) { unsigned r; asm volatile("v_cvt_pk_bf16_f32 %0, %1, %2" : "=v"(r) : "v"(lo), "v"(hi)); return r; }
; DI f32x4 mmaT(bf16x8 a_m, bf16x8 b_n, f32x4 c) { return __builtin_amdgcn_mfma_f32_16x16x32_bf16(b_n, a_m, c, 0, 0, 0); }
; DI void ret_out_unit(const Params& p, int hf, int bl, int c, int hd, unsigned char* shm, int tid, bool dry = false) {
;     ...
;   uint4 stv0, stv1, stv2, stv3; uint2 gv8[8];
;   {
;     const bf16_t* st = (const bf16_t*)(wsb + WS_RST) + (size_t)((bl * 64 + c) * 4 + hd) * 16384;
;     { const int e0 = tid >> 3, dg = tid & 7; stv0 = *(const uint4*)(st + e0 * 128 + dg * 16); stv1 = *(const uint4*)(st + e0 * 128 + dg * 16 + 8); stv2 = *(const uint4*)(st + (e0 + 64) * 128 + dg * 16); stv3 = *(const uint4*)(st + (e0 + 64) * 128 + dg * 16 + 8); }
;     const bf16_t* gp0 = projb + (size_t)(c * 128 + i_row) * NP + C_RG + hd * 128 + 4 * fq;
; #pragma unroll
;     for (int n = 0; n < 8; ++n) gv8[n] = *(const uint2*)(gp0 + 16 * n);
;   }
;   {
;     bf16x8 aq[4];
; #pragma unroll
;     for (int ks = 0; ks < 4; ++ks) aq[ks] = ldf(sQ, LD, 16 * wid, 32 * ks, fr, fq);
; #pragma unroll
;     for (int n = 0; n < 8; ++n) {
;       if (n <= (wid | 1)) {
;         uint2 w; w.x = 0u; w.y = 0u;
;         if (n <= wid) {
;           f32x4 s = (f32x4){0.f, 0.f, 0.f, 0.f};
; #pragma unroll
;           for (int ks = 0; ks < 4; ++ks) s = mmaT(aq[ks], ldf(sK, LD, 16 * n, 32 * ks, fr, fq), s);
;           float r[4];
; #pragma unroll
;           for (int j = 0; j < 4; ++j) { const int d = i_row - (16 * n + 4 * fq + j); r[j] = (d >= 0) ? s[j] * __expf(lg * (float)d) : 0.f; }
;           w.x = pk2(r[0], r[1]); w.y = pk2(r[2], r[3]);
;         }
;         *(uint2*)(sS + i_row * LD + 16 * n + 4 * fq) = w;
;       }
;     }
	global_load_dwordx4 v[0:3], v[4:5], off offset:16
	s_nop 0
	global_load_dwordx4 v[4:7], v[4:5], off
	s_nop 0
	global_load_dwordx4 v[8:11], v[12:13], off offset:16
	s_nop 0
	global_load_dwordx4 v[12:15], v[12:13], off
	s_nop 0
	global_load_dwordx2 v[64:65], v[16:17], off offset:1024
	global_load_dwordx2 v[62:63], v[48:49], off offset:32
	global_load_dwordx2 v[60:61], v[48:49], off offset:64
	global_load_dwordx2 v[58:59], v[48:49], off offset:96
	global_load_dwordx2 v[56:57], v[48:49], off offset:128
	global_load_dwordx2 v[54:55], v[48:49], off offset:160
	global_load_dwordx2 v[52:53], v[48:49], off offset:192
	global_load_dwordx2 v[50:51], v[48:49], off offset:224
	s_mov_b32 s0, 0x800000
	v_cmp_gt_f32_e32 vcc, s0, v32
	s_and_b64 s[0:1], vcc, exec
	s_cselect_b32 s0, 32, 0
	v_ldexp_f32 v32, v32, s0
	v_log_f32_e32 v32, v32
	v_and_b32_e32 v35, 48, v66
	v_add_u32_e32 v16, v70, v35
	ds_read_b128 v[28:31], v16
	ds_read_b128 v[24:27], v16 offset:64
	ds_read_b128 v[20:23], v16 offset:128
	ds_read_b128 v[16:19], v16 offset:192
	v_mul_f32_e32 v37, 0x3f317217, v32
	s_mov_b32 s0, 0x3f317217
	v_fma_f32 v37, v32, s0, -v37
	v_fmac_f32_e32 v37, 0x3377d1cf, v32
	s_mov_b32 s0, 0x7f800000
	v_fmac_f32_e32 v37, 0x3f317217, v32
	v_cmp_lt_f32_e64 s[0:1], |v32|, s0
	v_add_u32_e32 v38, 32, v35
	s_nop 0
	v_cndmask_b32_e64 v32, v32, v37, s[0:1]
	v_cndmask_b32_e32 v37, 0, v201, vcc
	v_readlane_b32 s0, v254, 1
	v_sub_f32_e32 v69, v32, v37
	v_cmp_lt_i32_e32 vcc, -1, v73
	v_add3_u32 v37, s0, v33, v34
	s_and_saveexec_b64 s[0:1], vcc
	s_cbranch_execz .LBB0_439
	v_mad_u32_u24 v39, v74, s66, v38
	ds_read_b128 v[32:35], v39 offset:34816
	ds_read_b128 v[40:43], v39 offset:34880
	s_waitcnt lgkmcnt(1)
	v_mfma_f32_16x16x32_bf16 v[32:35], v[32:35], v[28:31], 0
	s_waitcnt lgkmcnt(0)
	v_mfma_f32_16x16x32_bf16 v[32:35], v[40:43], v[24:27], v[32:35]
	ds_read_b128 v[40:43], v39 offset:34944
	s_waitcnt lgkmcnt(0)
	v_mfma_f32_16x16x32_bf16 v[32:35], v[40:43], v[20:23], v[32:35]
	ds_read_b128 v[40:43], v39 offset:35008
	v_sub_u32_e32 v39, v68, v36
	v_cmp_lt_i32_e32 vcc, -1, v39
	v_cvt_f32_u32_e32 v39, v39
	s_waitcnt lgkmcnt(0)
	v_mfma_f32_16x16x32_bf16 v[32:35], v[40:43], v[16:19], v[32:35]
	v_mul_f32_e32 v39, v69, v39
	v_mul_f32_e32 v39, 0x3fb8aa3b, v39
	v_exp_f32_e32 v39, v39
	s_nop 4
	v_mul_f32_e32 v32, v39, v32
	v_xad_u32 v39, v36, -1, v68
	v_cndmask_b32_e32 v32, 0, v32, vcc
	v_cmp_lt_i32_e32 vcc, -1, v39
	v_cvt_f32_u32_e32 v39, v39
	v_mul_f32_e32 v39, v69, v39
	v_mul_f32_e32 v39, 0x3fb8aa3b, v39
	v_exp_f32_e32 v39, v39
	s_nop 0
	v_mul_f32_e32 v33, v39, v33
	v_or_b32_e32 v39, 2, v36
	v_sub_u32_e32 v39, v68, v39
	v_cndmask_b32_e32 v33, 0, v33, vcc
	v_cmp_lt_i32_e32 vcc, -1, v39
	v_cvt_f32_u32_e32 v39, v39
	v_cvt_pk_bf16_f32 v32, v32, v33
	v_mul_f32_e32 v39, v69, v39
	v_mul_f32_e32 v39, 0x3fb8aa3b, v39
	v_exp_f32_e32 v39, v39
	s_nop 0
	v_mul_f32_e32 v34, v39, v34
	v_or_b32_e32 v39, 3, v36
	v_sub_u32_e32 v39, v68, v39
	v_cndmask_b32_e32 v34, 0, v34, vcc
	v_cmp_lt_i32_e32 vcc, -1, v39
	v_cvt_f32_u32_e32 v39, v39
	v_mul_f32_e32 v39, v69, v39
	v_mul_f32_e32 v39, 0x3fb8aa3b, v39
	v_exp_f32_e32 v39, v39
	s_nop 0
	v_mul_f32_e32 v35, v39, v35
	v_cndmask_b32_e32 v35, 0, v35, vcc
	v_cvt_pk_bf16_f32 v33, v34, v35
	ds_write_b64 v37, v[32:33]
	v_cmp_lt_u32_e32 vcc, 63, v66
	v_mov_b32_e32 v32, 0
	v_mov_b32_e32 v33, 0
	s_and_saveexec_b64 s[4:5], vcc
	s_cbranch_execz .LBB0_438
	v_add_u32_e32 v39, v38, v71
	ds_read_b128 v[32:35], v39 offset:39168
	ds_read_b128 v[40:43], v39 offset:39232
	s_waitcnt lgkmcnt(1)
	v_mfma_f32_16x16x32_bf16 v[32:35], v[32:35], v[28:31], 0
	s_waitcnt lgkmcnt(0)
	v_mfma_f32_16x16x32_bf16 v[32:35], v[40:43], v[24:27], v[32:35]
	ds_read_b128 v[40:43], v39 offset:39296
	s_waitcnt lgkmcnt(0)
	v_mfma_f32_16x16x32_bf16 v[32:35], v[40:43], v[20:23], v[32:35]
	ds_read_b128 v[40:43], v39 offset:39360
	v_or_b32_e32 v39, 16, v36
	v_sub_u32_e32 v39, v68, v39
	v_cmp_lt_i32_e32 vcc, -1, v39
	v_cvt_f32_u32_e32 v39, v39
	s_waitcnt lgkmcnt(0)
	v_mfma_f32_16x16x32_bf16 v[32:35], v[40:43], v[16:19], v[32:35]
	v_mul_f32_e32 v39, v69, v39
	v_mul_f32_e32 v39, 0x3fb8aa3b, v39
	v_exp_f32_e32 v39, v39
	s_nop 4
	v_mul_f32_e32 v32, v39, v32
	v_or_b32_e32 v39, 17, v36
	v_sub_u32_e32 v39, v68, v39
	v_cndmask_b32_e32 v32, 0, v32, vcc
	v_cmp_lt_i32_e32 vcc, -1, v39
	v_cvt_f32_u32_e32 v39, v39
	v_mul_f32_e32 v39, v69, v39
	v_mul_f32_e32 v39, 0x3fb8aa3b, v39
	v_exp_f32_e32 v39, v39
	s_nop 0
	v_mul_f32_e32 v33, v39, v33
	v_or_b32_e32 v39, 18, v36
	v_sub_u32_e32 v39, v68, v39
	v_cndmask_b32_e32 v33, 0, v33, vcc
	v_cmp_lt_i32_e32 vcc, -1, v39
	v_cvt_f32_u32_e32 v39, v39
	v_cvt_pk_bf16_f32 v32, v32, v33
	v_mul_f32_e32 v39, v69, v39
	v_mul_f32_e32 v39, 0x3fb8aa3b, v39
	v_exp_f32_e32 v39, v39
	s_nop 0
	v_mul_f32_e32 v34, v39, v34
	v_or_b32_e32 v39, 19, v36
	v_sub_u32_e32 v39, v68, v39
	v_cndmask_b32_e32 v34, 0, v34, vcc
	v_cmp_lt_i32_e32 vcc, -1, v39
	v_cvt_f32_u32_e32 v39, v39
	v_mul_f32_e32 v39, v69, v39
	v_mul_f32_e32 v39, 0x3fb8aa3b, v39
	v_exp_f32_e32 v39, v39
	s_nop 0
	v_mul_f32_e32 v35, v39, v35
	v_cndmask_b32_e32 v35, 0, v35, vcc
	v_cvt_pk_bf16_f32 v33, v34, v35

; DI void fox_unit(const Params& p, int hf, int bl, int fh, int qb, unsigned char* shm, int tid, bool dry = false) {
;     ...
;     if (kt + 1 < nkt) {
;       const size_t r = (size_t)((kt + 1) * 64 + skey) * NP;
;       kreg = *(const uint4*)(projb + r + C_FK + fh * 64 + sdg * 8); vreg = *(const uint4*)(projb + r + C_FV + fh * 64 + sdg * 8);
;       if (tid < 64) freg = (Fref - F[(kt + 1) * 64 + tid]) * LOG2E;
;     }
.LBB0_486:
	s_waitcnt vmcnt(1)
	v_add_u32_e32 v18, s18, v217
	v_mov_b64_e32 v[16:17], s[6:7]
	v_mad_i64_i32 v[16:17], s[4:5], v18, s65, v[16:17]
	v_lshl_add_u64 v[16:17], v[16:17], 0, s[2:3]
	v_lshl_add_u64 v[16:17], v[16:17], 0, v[160:161]
	v_add_co_u32_e32 v18, vcc, 0x1000, v16
	s_nop 1
	v_addc_co_u32_e32 v19, vcc, 0, v17, vcc
	s_waitcnt vmcnt(0)
	v_add_co_u32_e32 v20, vcc, 0x2000, v16
	s_nop 1
	v_addc_co_u32_e32 v21, vcc, 0, v17, vcc
	global_load_dwordx4 v[16:19], v[18:19], off offset:3072
	s_nop 0
	global_load_dwordx4 v[20:23], v[20:21], off
	s_and_saveexec_b64 s[4:5], s[0:1]
	s_cbranch_execz .LBB0_488
	v_add_u32_e32 v24, s18, v216
	v_ashrrev_i32_e32 v25, 31, v24
	v_lshl_add_u64 v[24:25], v[24:25], 2, s[8:9]
	global_load_dword v208, v[24:25], off

; DI void fox_unit(const Params& p, int hf, int bl, int fh, int qb, unsigned char* shm, int tid, bool dry = false) {
;     ...
;     if (kt + 1 < nkt) {
;       bf16_t* nK = (bf16_t*)(shm + (st ^ 1) * STG); bf16_t* nV = nK + 64 * 72; float* nF = (float*)(nV + 64 * 72);
;       *(uint4*)((unsigned char*)nK + kst) = kreg; *(uint4*)(nV + skey * 72 + sdg * 8) = vreg;
;       if (tid < 64) nF[tid] = freg;
;     }
.LBB0_494:
	s_xor_b32 s4, s21, 1
	s_mulk_i32 s4, 0x4900
	s_add_i32 s12, s4, 32
	s_waitcnt lgkmcnt(0)
	v_add_u32_e32 v24, s12, v210
	s_waitcnt vmcnt(1)
	ds_write_b128 v24, v[16:19]
	v_add3_u32 v24, s12, v211, v160
	s_waitcnt vmcnt(0)
	ds_write_b128 v24, v[20:23] offset:9216
	s_and_saveexec_b64 s[4:5], s[0:1]
	v_sub_f32_e32 v208, v192, v208
	v_lshl_add_u32 v24, v205, 2, s12
	v_mul_f32_e32 v208, 0x3fb8aa3b, v208
	ds_write_b32 v24, v208 offset:18432
	s_or_b64 exec, exec, s[4:5]

; DI void fox_unit(const Params& p, int hf, int bl, int fh, int qb, unsigned char* shm, int tid, bool dry = false) {
;     ...
;     if (kt + 1 < nkt) {
;       const size_t r = (size_t)((kt + 1) * 64 + skey) * NP;
;       kreg = *(const uint4*)(projb + r + C_FK + fh * 64 + sdg * 8); vreg = *(const uint4*)(projb + r + C_FV + fh * 64 + sdg * 8);
;       if (tid < 64) freg = (Fref - F[(kt + 1) * 64 + tid]) * LOG2E;
;     }
.LBB0_606:
	s_waitcnt vmcnt(1)
	v_add_u32_e32 v18, s17, v217
	v_mov_b64_e32 v[16:17], s[6:7]
	v_mad_i64_i32 v[16:17], s[4:5], v18, s65, v[16:17]
	v_lshl_add_u64 v[16:17], v[16:17], 0, s[2:3]
	v_lshl_add_u64 v[16:17], v[16:17], 0, v[160:161]
	v_add_co_u32_e32 v18, vcc, 0x1000, v16
	s_nop 1
	v_addc_co_u32_e32 v19, vcc, 0, v17, vcc
	s_waitcnt vmcnt(0)
	v_add_co_u32_e32 v20, vcc, 0x2000, v16
	s_nop 1
	v_addc_co_u32_e32 v21, vcc, 0, v17, vcc
	global_load_dwordx4 v[16:19], v[18:19], off offset:3072
	s_nop 0
	global_load_dwordx4 v[20:23], v[20:21], off
	s_and_saveexec_b64 s[4:5], s[0:1]
	s_cbranch_execz .LBB0_608
	v_add_u32_e32 v24, s17, v216
	v_ashrrev_i32_e32 v25, 31, v24
	v_lshl_add_u64 v[24:25], v[24:25], 2, s[8:9]
	global_load_dword v208, v[24:25], off

; DI void fox_unit(const Params& p, int hf, int bl, int fh, int qb, unsigned char* shm, int tid, bool dry = false) {
;     ...
;     if (kt + 1 < nkt) {
;       bf16_t* nK = (bf16_t*)(shm + (st ^ 1) * STG); bf16_t* nV = nK + 64 * 72; float* nF = (float*)(nV + 64 * 72);
;       *(uint4*)((unsigned char*)nK + kst) = kreg; *(uint4*)(nV + skey * 72 + sdg * 8) = vreg;
;       if (tid < 64) nF[tid] = freg;
;     }
.LBB0_614:
	s_xor_b32 s4, s20, 1
	s_mulk_i32 s4, 0x4900
	s_add_i32 s12, s4, 32
	s_waitcnt lgkmcnt(0)
	v_add_u32_e32 v24, s12, v210
	s_waitcnt vmcnt(1)
	ds_write_b128 v24, v[16:19]
	v_add3_u32 v24, s12, v211, v160
	s_waitcnt vmcnt(0)
	ds_write_b128 v24, v[20:23] offset:9216
	s_and_saveexec_b64 s[4:5], s[0:1]
	v_sub_f32_e32 v208, v192, v208
	v_lshl_add_u32 v24, v205, 2, s12
	v_mul_f32_e32 v208, 0x3fb8aa3b, v208
	ds_write_b32 v24, v208 offset:18432
	s_or_b64 exec, exec, s[4:5]

; template <int MODE>
; DI void gemm_phase(const Params& p, int layer, int hf, unsigned char* shmc, int tid) {
;     ...
;         {
;           const int r0 = tid >> 6, ch = tid & 63;
;           const int growb = hf * HROWS + brow + ai * HALF;
;           const float* gate = modb + (size_t)(layer * 4 + (growb >> 13)) * 3072 + 2048 + bcol + ch * 4;
;           const float4 g = *(const float4*)gate;
; #pragma unroll 4
;           for (int i = 0; i < 16; ++i) {
;             const int row = r0 + 8 * i;
;             const float4 v = *(const float4*)(shmc + row * 1040 + ch * 16);
;             const size_t off = (size_t)(growb + row) * DM + bcol + ch * 4;
;             const f32x4 xo = __builtin_nontemporal_load((const f32x4*)(xin + off));
;             f32x4 o; o[0] = xo[0] + g.x * v.x; o[1] = xo[1] + g.y * v.y; o[2] = xo[2] + g.z * v.z; o[3] = xo[3] + g.w * v.w;
;             __builtin_nontemporal_store(o, (f32x4*)(p.out + off));
;           }
;         }
.LBB0_705:
	v_lshlrev_b32_e32 v74, 10, v72
	v_add_u32_e32 v74, v74, v68
	v_lshlrev_b32_e32 v74, 2, v74
	s_mov_b64 s[98:99], s[6:7]
	global_load_dwordx4 v[76:79], v74, s[98:99] nt
	s_add_u32 s98, s98, 0x8000
	s_addc_u32 s99, s99, 0
	global_load_dwordx4 v[80:83], v74, s[98:99] nt
	s_add_u32 s98, s98, 0x8000
	s_addc_u32 s99, s99, 0
	global_load_dwordx4 v[84:87], v74, s[98:99] nt
	s_add_u32 s98, s98, 0x8000
	s_addc_u32 s99, s99, 0
	global_load_dwordx4 v[88:91], v74, s[98:99] nt
	s_add_u32 s98, s98, 0x8000
	s_addc_u32 s99, s99, 0
	global_load_dwordx4 v[92:95], v74, s[98:99] nt
	s_add_u32 s98, s98, 0x8000
	s_addc_u32 s99, s99, 0
	global_load_dwordx4 v[96:99], v74, s[98:99] nt
	s_add_u32 s98, s98, 0x8000
	s_addc_u32 s99, s99, 0
	global_load_dwordx4 v[100:103], v74, s[98:99] nt
	s_add_u32 s98, s98, 0x8000
	s_addc_u32 s99, s99, 0
	global_load_dwordx4 v[104:107], v74, s[98:99] nt
	s_add_u32 s98, s98, 0x8000
	s_addc_u32 s99, s99, 0
	global_load_dwordx4 v[108:111], v74, s[98:99] nt
	s_add_u32 s98, s98, 0x8000
	s_addc_u32 s99, s99, 0
	global_load_dwordx4 v[112:115], v74, s[98:99] nt
	s_add_u32 s98, s98, 0x8000
	s_addc_u32 s99, s99, 0
	global_load_dwordx4 v[116:119], v74, s[98:99] nt
	s_add_u32 s98, s98, 0x8000
	s_addc_u32 s99, s99, 0
	global_load_dwordx4 v[120:123], v74, s[98:99] nt
	s_add_u32 s98, s98, 0x8000
	s_addc_u32 s99, s99, 0
	global_load_dwordx4 v[124:127], v74, s[98:99] nt
	s_add_u32 s98, s98, 0x8000
	s_addc_u32 s99, s99, 0
	global_load_dwordx4 v[128:131], v74, s[98:99] nt
	s_add_u32 s98, s98, 0x8000
	s_addc_u32 s99, s99, 0
	global_load_dwordx4 v[132:135], v74, s[98:99] nt
	s_add_u32 s98, s98, 0x8000
	s_addc_u32 s99, s99, 0
	global_load_dwordx4 v[136:139], v74, s[98:99] nt
	s_mov_b64 s[98:99], s[36:37]
	ds_read_b128 v[140:143], v73
	s_waitcnt vmcnt(15) lgkmcnt(0)
	v_pk_fma_f32 v[78:79], v[66:67], v[142:143], v[78:79]
	v_pk_fma_f32 v[76:77], v[64:65], v[140:141], v[76:77]
	global_store_dwordx4 v74, v[76:79], s[98:99] nt
	s_add_u32 s98, s98, 0x8000
	s_addc_u32 s99, s99, 0
	ds_read_b128 v[140:143], v73 offset:8320
	s_waitcnt vmcnt(15) lgkmcnt(0)
	v_pk_fma_f32 v[82:83], v[66:67], v[142:143], v[82:83]
	v_pk_fma_f32 v[80:81], v[64:65], v[140:141], v[80:81]
	global_store_dwordx4 v74, v[80:83], s[98:99] nt
	s_add_u32 s98, s98, 0x8000
	s_addc_u32 s99, s99, 0
	ds_read_b128 v[140:143], v73 offset:16640
	s_waitcnt vmcnt(15) lgkmcnt(0)
	v_pk_fma_f32 v[86:87], v[66:67], v[142:143], v[86:87]
	v_pk_fma_f32 v[84:85], v[64:65], v[140:141], v[84:85]
	global_store_dwordx4 v74, v[84:87], s[98:99] nt
	s_add_u32 s98, s98, 0x8000
	s_addc_u32 s99, s99, 0
	ds_read_b128 v[140:143], v73 offset:24960
	v_add_u32_e32 v73, 0x8200, v73
	s_waitcnt vmcnt(15) lgkmcnt(0)
	v_pk_fma_f32 v[90:91], v[66:67], v[142:143], v[90:91]
	v_pk_fma_f32 v[88:89], v[64:65], v[140:141], v[88:89]
	global_store_dwordx4 v74, v[88:91], s[98:99] nt
	s_add_u32 s98, s98, 0x8000
	s_addc_u32 s99, s99, 0
	ds_read_b128 v[140:143], v73
	s_waitcnt vmcnt(15) lgkmcnt(0)
	v_pk_fma_f32 v[94:95], v[66:67], v[142:143], v[94:95]
	v_pk_fma_f32 v[92:93], v[64:65], v[140:141], v[92:93]
	global_store_dwordx4 v74, v[92:95], s[98:99] nt
	s_add_u32 s98, s98, 0x8000
	s_addc_u32 s99, s99, 0
	ds_read_b128 v[140:143], v73 offset:8320
	s_waitcnt vmcnt(15) lgkmcnt(0)
	v_pk_fma_f32 v[98:99], v[66:67], v[142:143], v[98:99]
	v_pk_fma_f32 v[96:97], v[64:65], v[140:141], v[96:97]
	global_store_dwordx4 v74, v[96:99], s[98:99] nt
	s_add_u32 s98, s98, 0x8000
	s_addc_u32 s99, s99, 0
	ds_read_b128 v[140:143], v73 offset:16640
	s_waitcnt vmcnt(15) lgkmcnt(0)
	v_pk_fma_f32 v[102:103], v[66:67], v[142:143], v[102:103]
	v_pk_fma_f32 v[100:101], v[64:65], v[140:141], v[100:101]
	global_store_dwordx4 v74, v[100:103], s[98:99] nt
	s_add_u32 s98, s98, 0x8000
	s_addc_u32 s99, s99, 0
	ds_read_b128 v[140:143], v73 offset:24960
	v_add_u32_e32 v73, 0x8200, v73
	s_waitcnt vmcnt(15) lgkmcnt(0)
	v_pk_fma_f32 v[106:107], v[66:67], v[142:143], v[106:107]
	v_pk_fma_f32 v[104:105], v[64:65], v[140:141], v[104:105]
	global_store_dwordx4 v74, v[104:107], s[98:99] nt
	s_add_u32 s98, s98, 0x8000
	s_addc_u32 s99, s99, 0
	ds_read_b128 v[140:143], v73
	s_waitcnt vmcnt(15) lgkmcnt(0)
	v_pk_fma_f32 v[110:111], v[66:67], v[142:143], v[110:111]
	v_pk_fma_f32 v[108:109], v[64:65], v[140:141], v[108:109]
	global_store_dwordx4 v74, v[108:111], s[98:99] nt
	s_add_u32 s98, s98, 0x8000
	s_addc_u32 s99, s99, 0
	ds_read_b128 v[140:143], v73 offset:8320
	s_waitcnt vmcnt(15) lgkmcnt(0)
	v_pk_fma_f32 v[114:115], v[66:67], v[142:143], v[114:115]
	v_pk_fma_f32 v[112:113], v[64:65], v[140:141], v[112:113]
	global_store_dwordx4 v74, v[112:115], s[98:99] nt
	s_add_u32 s98, s98, 0x8000
	s_addc_u32 s99, s99, 0
	ds_read_b128 v[140:143], v73 offset:16640
	s_waitcnt vmcnt(15) lgkmcnt(0)
	v_pk_fma_f32 v[118:119], v[66:67], v[142:143], v[118:119]
	v_pk_fma_f32 v[116:117], v[64:65], v[140:141], v[116:117]
	global_store_dwordx4 v74, v[116:119], s[98:99] nt
	s_add_u32 s98, s98, 0x8000
	s_addc_u32 s99, s99, 0
	ds_read_b128 v[140:143], v73 offset:24960
	v_add_u32_e32 v73, 0x8200, v73
	s_waitcnt vmcnt(15) lgkmcnt(0)
	v_pk_fma_f32 v[122:123], v[66:67], v[142:143], v[122:123]
	v_pk_fma_f32 v[120:121], v[64:65], v[140:141], v[120:121]
	global_store_dwordx4 v74, v[120:123], s[98:99] nt
	s_add_u32 s98, s98, 0x8000
	s_addc_u32 s99, s99, 0
	ds_read_b128 v[140:143], v73
	s_waitcnt vmcnt(15) lgkmcnt(0)
	v_pk_fma_f32 v[126:127], v[66:67], v[142:143], v[126:127]
	v_pk_fma_f32 v[124:125], v[64:65], v[140:141], v[124:125]
	global_store_dwordx4 v74, v[124:127], s[98:99] nt
	s_add_u32 s98, s98, 0x8000
	s_addc_u32 s99, s99, 0
	ds_read_b128 v[140:143], v73 offset:8320
	s_waitcnt vmcnt(15) lgkmcnt(0)
	v_pk_fma_f32 v[130:131], v[66:67], v[142:143], v[130:131]
	v_pk_fma_f32 v[128:129], v[64:65], v[140:141], v[128:129]
	global_store_dwordx4 v74, v[128:131], s[98:99] nt
	s_add_u32 s98, s98, 0x8000
	s_addc_u32 s99, s99, 0
	ds_read_b128 v[140:143], v73 offset:16640
	s_waitcnt vmcnt(15) lgkmcnt(0)
	v_pk_fma_f32 v[134:135], v[66:67], v[142:143], v[134:135]
	v_pk_fma_f32 v[132:133], v[64:65], v[140:141], v[132:133]
	global_store_dwordx4 v74, v[132:135], s[98:99] nt
	s_add_u32 s98, s98, 0x8000
	s_addc_u32 s99, s99, 0
	ds_read_b128 v[140:143], v73 offset:24960
	s_waitcnt vmcnt(15) lgkmcnt(0)
	v_pk_fma_f32 v[138:139], v[66:67], v[142:143], v[138:139]
	v_pk_fma_f32 v[136:137], v[64:65], v[140:141], v[136:137]
	global_store_dwordx4 v74, v[136:139], s[98:99] nt
	s_barrier
; template <int MODE>
; DI void gemm_phase(const Params& p, int layer, int hf, unsigned char* shmc, int tid) {
;     ...
;       for (int ai = 0; ai < 2; ++ai) {
; #pragma unroll
;         for (int m = 0; m < 4; ++m) {
;           unsigned char* rp = shmc + (wr * 64 + m * 16 + fr) * 1040 + (wc * 32 + fq * 4) * 4;
; #pragma unroll
;           for (int bj = 0; bj < 2; ++bj)
; #pragma unroll
;             for (int n = 0; n < 2; ++n) *(f32x4*)(rp + (bj * HALF + n * 16) * 4) = acc[ai][bj][m][n];
;         }
;         __syncthreads();
;         {
;           const int r0 = tid >> 6, ch = tid & 63;
;           const int growb = hf * HROWS + brow + ai * HALF;
;           const float* gate = modb + (size_t)(layer * 4 + (growb >> 13)) * 3072 + 2048 + bcol + ch * 4;
;           const float4 g = *(const float4*)gate;
	ds_write_b128 v177, v[12:15]
	ds_write_b128 v177, v[8:11] offset:64
	ds_write_b128 v177, v[32:35] offset:512
	ds_write_b128 v177, v[36:39] offset:576
	ds_write_b128 v177, v[4:7] offset:16640
	ds_write_b128 v177, v[0:3] offset:16704
	ds_write_b128 v177, v[40:43] offset:17152
	ds_write_b128 v177, v[44:47] offset:17216
	ds_write_b128 v177, v[16:19] offset:33280
	ds_write_b128 v177, v[20:23] offset:33344
	ds_write_b128 v177, v[48:51] offset:33792
	ds_write_b128 v177, v[52:55] offset:33856
	ds_write_b128 v177, v[24:27] offset:49920
	ds_write_b128 v177, v[28:31] offset:49984
	ds_write_b128 v177, v[56:59] offset:50432
	ds_write_b128 v177, v[60:63] offset:50496
	s_waitcnt lgkmcnt(0)
	s_barrier
	global_load_dwordx4 v[0:3], v[70:71], off
	s_mov_b32 s4, 0
	v_mov_b32_e32 v4, v176
; template <int MODE>
; DI void gemm_phase(const Params& p, int layer, int hf, unsigned char* shmc, int tid) {
;     ...
;         {
;           const int r0 = tid >> 6, ch = tid & 63;
;           const int growb = hf * HROWS + brow + ai * HALF;
;           const float* gate = modb + (size_t)(layer * 4 + (growb >> 13)) * 3072 + 2048 + bcol + ch * 4;
;           const float4 g = *(const float4*)gate;
; #pragma unroll 4
;           for (int i = 0; i < 16; ++i) {
;             const int row = r0 + 8 * i;
;             const float4 v = *(const float4*)(shmc + row * 1040 + ch * 16);
;             const size_t off = (size_t)(growb + row) * DM + bcol + ch * 4;
;             const f32x4 xo = __builtin_nontemporal_load((const f32x4*)(xin + off));
;             f32x4 o; o[0] = xo[0] + g.x * v.x; o[1] = xo[1] + g.y * v.y; o[2] = xo[2] + g.z * v.z; o[3] = xo[3] + g.w * v.w;
;             __builtin_nontemporal_store(o, (f32x4*)(p.out + off));
;           }
;         }
.LBB0_707:
	v_add_u32_e32 v74, 0x80, v72
	v_lshlrev_b32_e32 v74, 10, v74
	v_add_u32_e32 v74, v74, v68
	v_lshlrev_b32_e32 v74, 2, v74
	s_mov_b64 s[98:99], s[6:7]
	global_load_dwordx4 v[76:79], v74, s[98:99] nt
	s_add_u32 s98, s98, 0x8000
	s_addc_u32 s99, s99, 0
	global_load_dwordx4 v[80:83], v74, s[98:99] nt
	s_add_u32 s98, s98, 0x8000
	s_addc_u32 s99, s99, 0
	global_load_dwordx4 v[84:87], v74, s[98:99] nt
	s_add_u32 s98, s98, 0x8000
	s_addc_u32 s99, s99, 0
	global_load_dwordx4 v[88:91], v74, s[98:99] nt
	s_add_u32 s98, s98, 0x8000
	s_addc_u32 s99, s99, 0
	global_load_dwordx4 v[92:95], v74, s[98:99] nt
	s_add_u32 s98, s98, 0x8000
	s_addc_u32 s99, s99, 0
	global_load_dwordx4 v[96:99], v74, s[98:99] nt
	s_add_u32 s98, s98, 0x8000
	s_addc_u32 s99, s99, 0
	global_load_dwordx4 v[100:103], v74, s[98:99] nt
	s_add_u32 s98, s98, 0x8000
	s_addc_u32 s99, s99, 0
	global_load_dwordx4 v[104:107], v74, s[98:99] nt
	s_add_u32 s98, s98, 0x8000
	s_addc_u32 s99, s99, 0
	global_load_dwordx4 v[108:111], v74, s[98:99] nt
	s_add_u32 s98, s98, 0x8000
	s_addc_u32 s99, s99, 0
	global_load_dwordx4 v[112:115], v74, s[98:99] nt
	s_add_u32 s98, s98, 0x8000
	s_addc_u32 s99, s99, 0
	global_load_dwordx4 v[116:119], v74, s[98:99] nt
	s_add_u32 s98, s98, 0x8000
	s_addc_u32 s99, s99, 0
	global_load_dwordx4 v[120:123], v74, s[98:99] nt
	s_add_u32 s98, s98, 0x8000
	s_addc_u32 s99, s99, 0
	global_load_dwordx4 v[124:127], v74, s[98:99] nt
	s_add_u32 s98, s98, 0x8000
	s_addc_u32 s99, s99, 0
	global_load_dwordx4 v[128:131], v74, s[98:99] nt
	s_add_u32 s98, s98, 0x8000
	s_addc_u32 s99, s99, 0
	global_load_dwordx4 v[132:135], v74, s[98:99] nt
	s_add_u32 s98, s98, 0x8000
	s_addc_u32 s99, s99, 0
	global_load_dwordx4 v[136:139], v74, s[98:99] nt
	s_mov_b64 s[98:99], s[36:37]
	ds_read_b128 v[140:143], v4
	s_waitcnt vmcnt(15) lgkmcnt(0)
	v_pk_fma_f32 v[78:79], v[2:3], v[142:143], v[78:79]
	v_pk_fma_f32 v[76:77], v[0:1], v[140:141], v[76:77]
	global_store_dwordx4 v74, v[76:79], s[98:99] nt
	s_add_u32 s98, s98, 0x8000
	s_addc_u32 s99, s99, 0
	ds_read_b128 v[140:143], v4 offset:8320
	s_waitcnt vmcnt(15) lgkmcnt(0)
	v_pk_fma_f32 v[82:83], v[2:3], v[142:143], v[82:83]
	v_pk_fma_f32 v[80:81], v[0:1], v[140:141], v[80:81]
	global_store_dwordx4 v74, v[80:83], s[98:99] nt
	s_add_u32 s98, s98, 0x8000
	s_addc_u32 s99, s99, 0
	ds_read_b128 v[140:143], v4 offset:16640
	s_waitcnt vmcnt(15) lgkmcnt(0)
	v_pk_fma_f32 v[86:87], v[2:3], v[142:143], v[86:87]
	v_pk_fma_f32 v[84:85], v[0:1], v[140:141], v[84:85]
	global_store_dwordx4 v74, v[84:87], s[98:99] nt
	s_add_u32 s98, s98, 0x8000
	s_addc_u32 s99, s99, 0
	ds_read_b128 v[140:143], v4 offset:24960
	v_add_u32_e32 v4, 0x8200, v4
	s_waitcnt vmcnt(15) lgkmcnt(0)
	v_pk_fma_f32 v[90:91], v[2:3], v[142:143], v[90:91]
	v_pk_fma_f32 v[88:89], v[0:1], v[140:141], v[88:89]
	global_store_dwordx4 v74, v[88:91], s[98:99] nt
	s_add_u32 s98, s98, 0x8000
	s_addc_u32 s99, s99, 0
	ds_read_b128 v[140:143], v4
	s_waitcnt vmcnt(15) lgkmcnt(0)
	v_pk_fma_f32 v[94:95], v[2:3], v[142:143], v[94:95]
	v_pk_fma_f32 v[92:93], v[0:1], v[140:141], v[92:93]
	global_store_dwordx4 v74, v[92:95], s[98:99] nt
	s_add_u32 s98, s98, 0x8000
	s_addc_u32 s99, s99, 0
	ds_read_b128 v[140:143], v4 offset:8320
	s_waitcnt vmcnt(15) lgkmcnt(0)
	v_pk_fma_f32 v[98:99], v[2:3], v[142:143], v[98:99]
	v_pk_fma_f32 v[96:97], v[0:1], v[140:141], v[96:97]
	global_store_dwordx4 v74, v[96:99], s[98:99] nt
	s_add_u32 s98, s98, 0x8000
	s_addc_u32 s99, s99, 0
	ds_read_b128 v[140:143], v4 offset:16640
	s_waitcnt vmcnt(15) lgkmcnt(0)
	v_pk_fma_f32 v[102:103], v[2:3], v[142:143], v[102:103]
	v_pk_fma_f32 v[100:101], v[0:1], v[140:141], v[100:101]
	global_store_dwordx4 v74, v[100:103], s[98:99] nt
	s_add_u32 s98, s98, 0x8000
	s_addc_u32 s99, s99, 0
	ds_read_b128 v[140:143], v4 offset:24960
	v_add_u32_e32 v4, 0x8200, v4
	s_waitcnt vmcnt(15) lgkmcnt(0)
	v_pk_fma_f32 v[106:107], v[2:3], v[142:143], v[106:107]
	v_pk_fma_f32 v[104:105], v[0:1], v[140:141], v[104:105]
	global_store_dwordx4 v74, v[104:107], s[98:99] nt
	s_add_u32 s98, s98, 0x8000
	s_addc_u32 s99, s99, 0
	ds_read_b128 v[140:143], v4
	s_waitcnt vmcnt(15) lgkmcnt(0)
	v_pk_fma_f32 v[110:111], v[2:3], v[142:143], v[110:111]
	v_pk_fma_f32 v[108:109], v[0:1], v[140:141], v[108:109]
	global_store_dwordx4 v74, v[108:111], s[98:99] nt
	s_add_u32 s98, s98, 0x8000
	s_addc_u32 s99, s99, 0
	ds_read_b128 v[140:143], v4 offset:8320
	s_waitcnt vmcnt(15) lgkmcnt(0)
	v_pk_fma_f32 v[114:115], v[2:3], v[142:143], v[114:115]
	v_pk_fma_f32 v[112:113], v[0:1], v[140:141], v[112:113]
	global_store_dwordx4 v74, v[112:115], s[98:99] nt
	s_add_u32 s98, s98, 0x8000
	s_addc_u32 s99, s99, 0
	ds_read_b128 v[140:143], v4 offset:16640
	s_waitcnt vmcnt(15) lgkmcnt(0)
	v_pk_fma_f32 v[118:119], v[2:3], v[142:143], v[118:119]
	v_pk_fma_f32 v[116:117], v[0:1], v[140:141], v[116:117]
	global_store_dwordx4 v74, v[116:119], s[98:99] nt
	s_add_u32 s98, s98, 0x8000
	s_addc_u32 s99, s99, 0
	ds_read_b128 v[140:143], v4 offset:24960
	v_add_u32_e32 v4, 0x8200, v4
	s_waitcnt vmcnt(15) lgkmcnt(0)
	v_pk_fma_f32 v[122:123], v[2:3], v[142:143], v[122:123]
	v_pk_fma_f32 v[120:121], v[0:1], v[140:141], v[120:121]
	global_store_dwordx4 v74, v[120:123], s[98:99] nt
	s_add_u32 s98, s98, 0x8000
	s_addc_u32 s99, s99, 0
	ds_read_b128 v[140:143], v4
	s_waitcnt vmcnt(15) lgkmcnt(0)
	v_pk_fma_f32 v[126:127], v[2:3], v[142:143], v[126:127]
	v_pk_fma_f32 v[124:125], v[0:1], v[140:141], v[124:125]
	global_store_dwordx4 v74, v[124:127], s[98:99] nt
	s_add_u32 s98, s98, 0x8000
	s_addc_u32 s99, s99, 0
	ds_read_b128 v[140:143], v4 offset:8320
	s_waitcnt vmcnt(15) lgkmcnt(0)
	v_pk_fma_f32 v[130:131], v[2:3], v[142:143], v[130:131]
	v_pk_fma_f32 v[128:129], v[0:1], v[140:141], v[128:129]
	global_store_dwordx4 v74, v[128:131], s[98:99] nt
	s_add_u32 s98, s98, 0x8000
	s_addc_u32 s99, s99, 0
	ds_read_b128 v[140:143], v4 offset:16640
	s_waitcnt vmcnt(15) lgkmcnt(0)
	v_pk_fma_f32 v[134:135], v[2:3], v[142:143], v[134:135]
	v_pk_fma_f32 v[132:133], v[0:1], v[140:141], v[132:133]
	global_store_dwordx4 v74, v[132:135], s[98:99] nt
	s_add_u32 s98, s98, 0x8000
	s_addc_u32 s99, s99, 0
	ds_read_b128 v[140:143], v4 offset:24960
	s_waitcnt vmcnt(15) lgkmcnt(0)
	v_pk_fma_f32 v[138:139], v[2:3], v[142:143], v[138:139]
	v_pk_fma_f32 v[136:137], v[0:1], v[140:141], v[136:137]
	global_store_dwordx4 v74, v[136:139], s[98:99] nt
	s_and_b64 vcc, exec, s[0:1]
	s_mov_b32 s6, s13
	s_mov_b32 s14, s12
	s_barrier
	s_cbranch_vccz .LBB0_690

; __global__ void __launch_bounds__(NTHR) mega(Params p) {
	.amdhsa_kernel _Z4mega6Params
		.amdhsa_group_segment_fixed_size 32
		.amdhsa_private_segment_fixed_size 0
		.amdhsa_kernarg_size 400
		.amdhsa_user_sgpr_count 2
		.amdhsa_user_sgpr_dispatch_ptr 0
		.amdhsa_user_sgpr_queue_ptr 0
		.amdhsa_user_sgpr_kernarg_segment_ptr 1
		.amdhsa_user_sgpr_dispatch_id 0
		.amdhsa_user_sgpr_kernarg_preload_length 0
		.amdhsa_user_sgpr_kernarg_preload_offset 0
		.amdhsa_user_sgpr_private_segment_size 0
		.amdhsa_uses_dynamic_stack 0
		.amdhsa_enable_private_segment 0
		.amdhsa_system_sgpr_workgroup_id_x 1
		.amdhsa_system_sgpr_workgroup_id_y 0
		.amdhsa_system_sgpr_workgroup_id_z 0
		.amdhsa_system_sgpr_workgroup_info 0
		.amdhsa_system_vgpr_workitem_id 2
		.amdhsa_next_free_vgpr 256
		.amdhsa_next_free_sgpr 102
		.amdhsa_accum_offset 256
		.amdhsa_reserve_vcc 1
		.amdhsa_float_round_mode_32 0
		.amdhsa_float_round_mode_16_64 0
		.amdhsa_float_denorm_mode_32 3
		.amdhsa_float_denorm_mode_16_64 3
		.amdhsa_dx10_clamp 1
		.amdhsa_ieee_mode 1
		.amdhsa_fp16_overflow 0
		.amdhsa_tg_split 0
		.amdhsa_exception_fp_ieee_invalid_op 0
		.amdhsa_exception_fp_denorm_src 0
		.amdhsa_exception_fp_ieee_div_zero 0
		.amdhsa_exception_fp_ieee_overflow 0
		.amdhsa_exception_fp_ieee_underflow 0
		.amdhsa_exception_fp_ieee_inexact 0
		.amdhsa_exception_int_div_zero 0
	.end_amdhsa_kernel

; __global__ void __launch_bounds__(NTHR) mega(Params p) {
amdhsa.kernels:
  - .agpr_count:     0
    .args:
      - .offset:         0
        .size:           144
        .value_kind:     by_value
      - .offset:         144
        .size:           4
        .value_kind:     hidden_block_count_x
      - .offset:         148
        .size:           4
        .value_kind:     hidden_block_count_y
      - .offset:         152
        .size:           4
        .value_kind:     hidden_block_count_z
      - .offset:         156
        .size:           2
        .value_kind:     hidden_group_size_x
      - .offset:         158
        .size:           2
        .value_kind:     hidden_group_size_y
      - .offset:         160
        .size:           2
        .value_kind:     hidden_group_size_z
      - .offset:         162
        .size:           2
        .value_kind:     hidden_remainder_x
      - .offset:         164
        .size:           2
        .value_kind:     hidden_remainder_y
      - .offset:         166
        .size:           2
        .value_kind:     hidden_remainder_z
      - .offset:         184
        .size:           8
        .value_kind:     hidden_global_offset_x
      - .offset:         192
        .size:           8
        .value_kind:     hidden_global_offset_y
      - .offset:         200
        .size:           8
        .value_kind:     hidden_global_offset_z
      - .offset:         208
        .size:           2
        .value_kind:     hidden_grid_dims
      - .offset:         232
        .size:           8
        .value_kind:     hidden_multigrid_sync_arg
      - .offset:         264
        .size:           4
        .value_kind:     hidden_dynamic_lds_size
    .group_segment_fixed_size: 32
    .kernarg_segment_align: 8
    .kernarg_segment_size: 400
    .language:       OpenCL C
    .language_version:
      - 2
      - 0
    .max_flat_workgroup_size: 512
    .name:           _Z4mega6Params
    .private_segment_fixed_size: 0
    .sgpr_count:     108
    .sgpr_spill_count: 243
    .symbol:         _Z4mega6Params.kd
    .uniform_work_group_size: 1
    .uses_dynamic_stack: false
    .vgpr_count:     256
    .vgpr_spill_count: 0
    .wavefront_size: 64
